# fast loop unrolled x2 with scalar-base DMA addressing; nt cache hint on P4 (W_in GEMM) epilogue stores
# speedup vs baseline: 1.0749x; 1.0176x over previous
.LBB0_220:
	s_cmp_lt_i32 s44, 4
	s_cselect_b64 s[20:21], -1, 0
	s_cmp_lt_u32 s10, 3
	s_cselect_b64 s[46:47], -1, 0
	s_or_b64 vcc, s[20:21], s[46:47]
	s_waitcnt lgkmcnt(0)
	v_cndmask_b32_e32 v178, 1.0, v201, vcc
	v_lshl_or_b32 v180, s44, 8, v195
	v_mov_b64_e32 v[182:183], s[16:17]
	v_ashrrev_i32_e32 v181, 31, v180
	v_mad_i64_i32 v[182:183], s[20:21], v176, s68, v[182:183]
	v_pk_mul_f32 v[148:149], v[178:179], v[148:149] op_sel_hi:[0,1]
	v_pk_mul_f32 v[146:147], v[178:179], v[146:147] op_sel_hi:[0,1]
	v_pk_mul_f32 v[152:153], v[178:179], v[152:153] op_sel_hi:[0,1]
	v_pk_mul_f32 v[150:151], v[178:179], v[150:151] op_sel_hi:[0,1]
	v_lshl_add_u64 v[182:183], v[180:181], 1, v[182:183]
	v_cvt_pk_bf16_f32 v146, v146, v147
	v_cvt_pk_bf16_f32 v147, v148, v149
	v_cvt_pk_bf16_f32 v148, v150, v151
	v_cvt_pk_bf16_f32 v149, v152, v153
	global_store_dwordx4 v[182:183], v[146:149], off nt
	v_mov_b64_e32 v[152:153], v[116:117]
	s_and_b64 vcc, exec, s[6:7]
	v_mov_b64_e32 v[148:149], v[120:121]
	v_mov_b64_e32 v[146:147], v[118:119]
	v_mov_b64_e32 v[150:151], v[114:115]
	s_cbranch_vccnz .LBB0_224
	v_and_b32_e32 v147, 64, v200
	v_xor_b32_e32 v146, 16, v200
	v_add_u32_e32 v147, 64, v147
	v_cmp_lt_i32_e32 vcc, v146, v147
	v_mov_b64_e32 v[152:153], v[116:117]
	v_mov_b64_e32 v[150:151], v[114:115]
	v_cndmask_b32_e32 v146, v200, v146, vcc
	v_lshlrev_b32_e32 v146, 2, v146
	ds_bpermute_b32 v188, v146, v118
	ds_bpermute_b32 v184, v146, v114
	ds_bpermute_b32 v189, v146, v119
	ds_bpermute_b32 v185, v146, v115
	ds_bpermute_b32 v190, v146, v120
	ds_bpermute_b32 v186, v146, v116
	ds_bpermute_b32 v191, v146, v121
	ds_bpermute_b32 v187, v146, v117
	v_mov_b64_e32 v[148:149], v[120:121]
	v_mov_b64_e32 v[146:147], v[118:119]
	s_and_saveexec_b64 s[46:47], s[2:3]
	s_cbranch_execz .LBB0_223
	s_waitcnt lgkmcnt(0)
	v_pk_mul_f32 v[146:147], v[166:167], v[190:191]
	v_pk_mul_f32 v[148:149], v[164:165], v[188:189]
	s_waitcnt vmcnt(0)
	v_pk_mul_f32 v[144:145], v[144:145], v[146:147]
	v_pk_mul_f32 v[142:143], v[142:143], v[148:149]
	v_pk_fma_f32 v[148:149], v[120:121], v[136:137], v[144:145]
	v_pk_fma_f32 v[146:147], v[118:119], v[134:135], v[142:143]
	v_pk_mul_f32 v[134:135], v[166:167], v[186:187]
	v_pk_mul_f32 v[136:137], v[164:165], v[184:185]
	v_pk_mul_f32 v[134:135], v[140:141], v[134:135]
	v_pk_mul_f32 v[136:137], v[138:139], v[136:137]
	v_pk_fma_f32 v[152:153], v[116:117], v[132:133], v[134:135]
	v_pk_fma_f32 v[150:151], v[114:115], v[130:131], v[136:137]

.LBB0_224:
	v_mov_b32_e32 v179, v178
	s_waitcnt vmcnt(0)
	v_mov_b32_e32 v130, v178
	v_mov_b32_e32 v131, v178
	v_pk_mul_f32 v[132:133], v[130:131], v[148:149]
	v_pk_mul_f32 v[134:135], v[178:179], v[146:147]
	v_pk_mul_f32 v[136:137], v[130:131], v[152:153]
	v_pk_mul_f32 v[138:139], v[178:179], v[150:151]
	v_cvt_pk_bf16_f32 v130, v134, v135
	v_cvt_pk_bf16_f32 v131, v132, v133
	v_cvt_pk_bf16_f32 v132, v138, v139
	v_cvt_pk_bf16_f32 v133, v136, v137
	global_store_dwordx4 v[182:183], v[130:133], off offset:256 nt
	v_or_b32_e32 v182, 16, v176
	s_and_b64 vcc, exec, s[6:7]
	v_ashrrev_i32_e32 v183, 31, v182
	s_cbranch_vccnz .LBB0_226
	v_lshlrev_b64 v[130:131], 6, v[182:183]
	v_lshl_add_u64 v[138:139], s[14:15], 0, v[130:131]
	global_load_dwordx4 v[134:137], v[138:139], off
	global_load_dwordx4 v[130:133], v[138:139], off offset:16
	global_load_dwordx4 v[142:145], v[138:139], off offset:32
	s_nop 0
	global_load_dwordx4 v[138:141], v[138:139], off offset:48
	s_branch .LBB0_227

.LBB0_231:
	s_waitcnt lgkmcnt(4)
	v_mov_b64_e32 v[184:185], s[16:17]
	v_mad_i64_i32 v[182:183], s[20:21], v182, s68, v[184:185]
	v_mov_b32_e32 v184, v178
	v_mov_b32_e32 v185, v178
	v_pk_mul_f32 v[148:149], v[184:185], v[148:149]
	v_pk_mul_f32 v[146:147], v[178:179], v[146:147]
	v_pk_mul_f32 v[152:153], v[184:185], v[152:153]
	v_pk_mul_f32 v[150:151], v[178:179], v[150:151]
	v_lshl_add_u64 v[182:183], v[180:181], 1, v[182:183]
	v_cvt_pk_bf16_f32 v146, v146, v147
	v_cvt_pk_bf16_f32 v147, v148, v149
	v_cvt_pk_bf16_f32 v148, v150, v151
	v_cvt_pk_bf16_f32 v149, v152, v153
	global_store_dwordx4 v[182:183], v[146:149], off nt
	v_mov_b64_e32 v[152:153], v[100:101]
	s_and_b64 vcc, exec, s[6:7]
	v_mov_b64_e32 v[148:149], v[104:105]
	v_mov_b64_e32 v[146:147], v[102:103]
	v_mov_b64_e32 v[150:151], v[98:99]
	s_cbranch_vccnz .LBB0_235
	v_and_b32_e32 v147, 64, v200
	v_xor_b32_e32 v146, 16, v200
	v_add_u32_e32 v147, 64, v147
	v_cmp_lt_i32_e32 vcc, v146, v147
	v_mov_b64_e32 v[152:153], v[100:101]
	v_mov_b64_e32 v[150:151], v[98:99]
	v_cndmask_b32_e32 v146, v200, v146, vcc
	v_lshlrev_b32_e32 v146, 2, v146
	s_waitcnt lgkmcnt(3)
	ds_bpermute_b32 v190, v146, v102
	s_waitcnt lgkmcnt(3)
	ds_bpermute_b32 v186, v146, v98
	s_waitcnt lgkmcnt(3)
	ds_bpermute_b32 v191, v146, v103
	s_waitcnt lgkmcnt(3)
	ds_bpermute_b32 v187, v146, v99
	ds_bpermute_b32 v192, v146, v104
	ds_bpermute_b32 v188, v146, v100
	ds_bpermute_b32 v193, v146, v105
	ds_bpermute_b32 v189, v146, v101
	v_mov_b64_e32 v[148:149], v[104:105]
	v_mov_b64_e32 v[146:147], v[102:103]
	s_and_saveexec_b64 s[46:47], s[2:3]
	s_cbranch_execz .LBB0_234
	s_waitcnt lgkmcnt(1)
	v_pk_mul_f32 v[146:147], v[166:167], v[192:193]
	v_pk_mul_f32 v[148:149], v[164:165], v[190:191]
	s_waitcnt vmcnt(2)
	v_pk_mul_f32 v[144:145], v[144:145], v[146:147]
	v_pk_mul_f32 v[142:143], v[142:143], v[148:149]
	v_pk_fma_f32 v[148:149], v[104:105], v[136:137], v[144:145]
	v_pk_fma_f32 v[146:147], v[102:103], v[134:135], v[142:143]
	s_waitcnt lgkmcnt(0)
	v_pk_mul_f32 v[134:135], v[166:167], v[188:189]
	v_pk_mul_f32 v[136:137], v[164:165], v[186:187]
	s_waitcnt vmcnt(1)
	v_pk_mul_f32 v[134:135], v[140:141], v[134:135]
	v_pk_mul_f32 v[136:137], v[138:139], v[136:137]
	v_pk_fma_f32 v[152:153], v[100:101], v[132:133], v[134:135]
	v_pk_fma_f32 v[150:151], v[98:99], v[130:131], v[136:137]

.LBB0_235:
	s_waitcnt vmcnt(3)
	v_pk_mul_f32 v[132:133], v[184:185], v[148:149]
	v_pk_mul_f32 v[130:131], v[178:179], v[146:147]
	v_pk_mul_f32 v[134:135], v[184:185], v[152:153]
	v_pk_mul_f32 v[136:137], v[178:179], v[150:151]
	v_cvt_pk_bf16_f32 v130, v130, v131
	v_cvt_pk_bf16_f32 v131, v132, v133
	v_cvt_pk_bf16_f32 v132, v136, v137
	v_cvt_pk_bf16_f32 v133, v134, v135
	global_store_dwordx4 v[182:183], v[130:133], off offset:256 nt
	v_or_b32_e32 v182, 32, v176
	s_and_b64 vcc, exec, s[6:7]
	v_ashrrev_i32_e32 v183, 31, v182
	s_cbranch_vccnz .LBB0_237
	v_lshlrev_b64 v[130:131], 6, v[182:183]
	s_waitcnt vmcnt(2)
	v_lshl_add_u64 v[138:139], s[14:15], 0, v[130:131]
	global_load_dwordx4 v[134:137], v[138:139], off
	global_load_dwordx4 v[130:133], v[138:139], off offset:16
	global_load_dwordx4 v[142:145], v[138:139], off offset:32
	s_nop 0
	global_load_dwordx4 v[138:141], v[138:139], off offset:48
	s_branch .LBB0_238

.LBB0_242:
	s_waitcnt lgkmcnt(4)
	v_mov_b64_e32 v[184:185], s[16:17]
	v_mad_i64_i32 v[182:183], s[20:21], v182, s68, v[184:185]
	v_mov_b32_e32 v184, v178
	v_mov_b32_e32 v185, v178
	v_pk_mul_f32 v[148:149], v[184:185], v[148:149]
	v_pk_mul_f32 v[146:147], v[178:179], v[146:147]
	v_pk_mul_f32 v[152:153], v[184:185], v[152:153]
	v_pk_mul_f32 v[150:151], v[178:179], v[150:151]
	v_lshl_add_u64 v[182:183], v[180:181], 1, v[182:183]
	v_cvt_pk_bf16_f32 v146, v146, v147
	v_cvt_pk_bf16_f32 v147, v148, v149
	v_cvt_pk_bf16_f32 v148, v150, v151
	v_cvt_pk_bf16_f32 v149, v152, v153
	global_store_dwordx4 v[182:183], v[146:149], off nt
	v_mov_b64_e32 v[152:153], v[84:85]
	s_and_b64 vcc, exec, s[6:7]
	v_mov_b64_e32 v[148:149], v[88:89]
	v_mov_b64_e32 v[146:147], v[86:87]
	v_mov_b64_e32 v[150:151], v[82:83]
	s_cbranch_vccnz .LBB0_246
	v_and_b32_e32 v147, 64, v200
	v_xor_b32_e32 v146, 16, v200
	v_add_u32_e32 v147, 64, v147
	v_cmp_lt_i32_e32 vcc, v146, v147
	v_mov_b64_e32 v[152:153], v[84:85]
	v_mov_b64_e32 v[150:151], v[82:83]
	v_cndmask_b32_e32 v146, v200, v146, vcc
	v_lshlrev_b32_e32 v146, 2, v146
	s_waitcnt lgkmcnt(3)
	ds_bpermute_b32 v190, v146, v86
	s_waitcnt lgkmcnt(3)
	ds_bpermute_b32 v186, v146, v82
	s_waitcnt lgkmcnt(3)
	ds_bpermute_b32 v191, v146, v87
	s_waitcnt lgkmcnt(3)
	ds_bpermute_b32 v187, v146, v83
	ds_bpermute_b32 v192, v146, v88
	ds_bpermute_b32 v188, v146, v84
	ds_bpermute_b32 v193, v146, v89
	ds_bpermute_b32 v189, v146, v85
	v_mov_b64_e32 v[148:149], v[88:89]
	v_mov_b64_e32 v[146:147], v[86:87]
	s_and_saveexec_b64 s[46:47], s[2:3]
	s_cbranch_execz .LBB0_245
	s_waitcnt lgkmcnt(1)
	v_pk_mul_f32 v[146:147], v[166:167], v[192:193]
	v_pk_mul_f32 v[148:149], v[164:165], v[190:191]
	s_waitcnt vmcnt(2)
	v_pk_mul_f32 v[144:145], v[144:145], v[146:147]
	v_pk_mul_f32 v[142:143], v[142:143], v[148:149]
	v_pk_fma_f32 v[148:149], v[88:89], v[136:137], v[144:145]
	v_pk_fma_f32 v[146:147], v[86:87], v[134:135], v[142:143]
	s_waitcnt lgkmcnt(0)
	v_pk_mul_f32 v[134:135], v[166:167], v[188:189]
	v_pk_mul_f32 v[136:137], v[164:165], v[186:187]
	s_waitcnt vmcnt(1)
	v_pk_mul_f32 v[134:135], v[140:141], v[134:135]
	v_pk_mul_f32 v[136:137], v[138:139], v[136:137]
	v_pk_fma_f32 v[152:153], v[84:85], v[132:133], v[134:135]
	v_pk_fma_f32 v[150:151], v[82:83], v[130:131], v[136:137]

.LBB0_246:
	s_waitcnt vmcnt(3)
	v_pk_mul_f32 v[132:133], v[184:185], v[148:149]
	v_pk_mul_f32 v[130:131], v[178:179], v[146:147]
	v_pk_mul_f32 v[134:135], v[184:185], v[152:153]
	v_pk_mul_f32 v[136:137], v[178:179], v[150:151]
	v_cvt_pk_bf16_f32 v130, v130, v131
	v_cvt_pk_bf16_f32 v131, v132, v133
	v_cvt_pk_bf16_f32 v132, v136, v137
	v_cvt_pk_bf16_f32 v133, v134, v135
	global_store_dwordx4 v[182:183], v[130:133], off offset:256 nt
	v_or_b32_e32 v182, 48, v176
	s_and_b64 vcc, exec, s[6:7]
	v_ashrrev_i32_e32 v183, 31, v182
	s_cbranch_vccnz .LBB0_248
	v_lshlrev_b64 v[130:131], 6, v[182:183]
	s_waitcnt vmcnt(2)
	v_lshl_add_u64 v[138:139], s[14:15], 0, v[130:131]
	global_load_dwordx4 v[134:137], v[138:139], off
	global_load_dwordx4 v[130:133], v[138:139], off offset:16
	global_load_dwordx4 v[142:145], v[138:139], off offset:32
	s_nop 0
	global_load_dwordx4 v[138:141], v[138:139], off offset:48
	s_branch .LBB0_249

.LBB0_253:
	s_waitcnt lgkmcnt(4)
	v_mov_b64_e32 v[184:185], s[16:17]
	v_mad_i64_i32 v[182:183], s[20:21], v182, s68, v[184:185]
	v_mov_b32_e32 v184, v178
	v_mov_b32_e32 v185, v178
	v_pk_mul_f32 v[148:149], v[184:185], v[148:149]
	v_pk_mul_f32 v[146:147], v[178:179], v[146:147]
	v_pk_mul_f32 v[152:153], v[184:185], v[152:153]
	v_pk_mul_f32 v[150:151], v[178:179], v[150:151]
	v_lshl_add_u64 v[182:183], v[180:181], 1, v[182:183]
	v_cvt_pk_bf16_f32 v146, v146, v147
	v_cvt_pk_bf16_f32 v147, v148, v149
	v_cvt_pk_bf16_f32 v148, v150, v151
	v_cvt_pk_bf16_f32 v149, v152, v153
	global_store_dwordx4 v[182:183], v[146:149], off nt
	v_mov_b64_e32 v[152:153], v[68:69]
	s_and_b64 vcc, exec, s[6:7]
	v_mov_b64_e32 v[148:149], v[72:73]
	v_mov_b64_e32 v[146:147], v[70:71]
	v_mov_b64_e32 v[150:151], v[66:67]
	s_cbranch_vccnz .LBB0_257
	v_and_b32_e32 v147, 64, v200
	v_xor_b32_e32 v146, 16, v200
	v_add_u32_e32 v147, 64, v147
	v_cmp_lt_i32_e32 vcc, v146, v147
	v_mov_b64_e32 v[152:153], v[68:69]
	v_mov_b64_e32 v[150:151], v[66:67]
	v_cndmask_b32_e32 v146, v200, v146, vcc
	v_lshlrev_b32_e32 v146, 2, v146
	s_waitcnt lgkmcnt(3)
	ds_bpermute_b32 v190, v146, v70
	s_waitcnt lgkmcnt(3)
	ds_bpermute_b32 v186, v146, v66
	s_waitcnt lgkmcnt(3)
	ds_bpermute_b32 v191, v146, v71
	s_waitcnt lgkmcnt(3)
	ds_bpermute_b32 v187, v146, v67
	ds_bpermute_b32 v192, v146, v72
	ds_bpermute_b32 v188, v146, v68
	ds_bpermute_b32 v193, v146, v73
	ds_bpermute_b32 v189, v146, v69
	v_mov_b64_e32 v[148:149], v[72:73]
	v_mov_b64_e32 v[146:147], v[70:71]
	s_and_saveexec_b64 s[46:47], s[2:3]
	s_cbranch_execz .LBB0_256
	s_waitcnt lgkmcnt(1)
	v_pk_mul_f32 v[146:147], v[166:167], v[192:193]
	v_pk_mul_f32 v[148:149], v[164:165], v[190:191]
	s_waitcnt vmcnt(2)
	v_pk_mul_f32 v[144:145], v[144:145], v[146:147]
	v_pk_mul_f32 v[142:143], v[142:143], v[148:149]
	v_pk_fma_f32 v[148:149], v[72:73], v[136:137], v[144:145]
	v_pk_fma_f32 v[146:147], v[70:71], v[134:135], v[142:143]
	s_waitcnt lgkmcnt(0)
	v_pk_mul_f32 v[134:135], v[166:167], v[188:189]
	v_pk_mul_f32 v[136:137], v[164:165], v[186:187]
	s_waitcnt vmcnt(1)
	v_pk_mul_f32 v[134:135], v[140:141], v[134:135]
	v_pk_mul_f32 v[136:137], v[138:139], v[136:137]
	v_pk_fma_f32 v[152:153], v[68:69], v[132:133], v[134:135]
	v_pk_fma_f32 v[150:151], v[66:67], v[130:131], v[136:137]

.LBB0_257:
	s_waitcnt vmcnt(3)
	v_pk_mul_f32 v[132:133], v[184:185], v[148:149]
	v_pk_mul_f32 v[130:131], v[178:179], v[146:147]
	v_pk_mul_f32 v[134:135], v[184:185], v[152:153]
	v_pk_mul_f32 v[136:137], v[178:179], v[150:151]
	v_cvt_pk_bf16_f32 v130, v130, v131
	v_cvt_pk_bf16_f32 v131, v132, v133
	v_cvt_pk_bf16_f32 v132, v136, v137
	v_cvt_pk_bf16_f32 v133, v134, v135
	global_store_dwordx4 v[182:183], v[130:133], off offset:256 nt
	v_add_u32_e32 v182, 0x80, v176
	s_and_b64 vcc, exec, s[6:7]
	v_ashrrev_i32_e32 v183, 31, v182
	s_cbranch_vccnz .LBB0_259
	v_lshlrev_b64 v[130:131], 6, v[182:183]
	s_waitcnt vmcnt(2)
	v_lshl_add_u64 v[138:139], s[14:15], 0, v[130:131]
	global_load_dwordx4 v[134:137], v[138:139], off
	global_load_dwordx4 v[130:133], v[138:139], off offset:16
	global_load_dwordx4 v[142:145], v[138:139], off offset:32
	s_nop 0
	global_load_dwordx4 v[138:141], v[138:139], off offset:48
	s_branch .LBB0_260

.LBB0_264:
	s_waitcnt lgkmcnt(4)
	v_mov_b64_e32 v[184:185], s[16:17]
	v_mad_i64_i32 v[182:183], s[20:21], v182, s68, v[184:185]
	v_mov_b32_e32 v184, v178
	v_mov_b32_e32 v185, v178
	v_pk_mul_f32 v[148:149], v[184:185], v[148:149]
	v_pk_mul_f32 v[146:147], v[178:179], v[146:147]
	v_pk_mul_f32 v[152:153], v[184:185], v[152:153]
	v_pk_mul_f32 v[150:151], v[178:179], v[150:151]
	v_lshl_add_u64 v[182:183], v[180:181], 1, v[182:183]
	v_cvt_pk_bf16_f32 v146, v146, v147
	v_cvt_pk_bf16_f32 v147, v148, v149
	v_cvt_pk_bf16_f32 v148, v150, v151
	v_cvt_pk_bf16_f32 v149, v152, v153
	global_store_dwordx4 v[182:183], v[146:149], off nt
	v_mov_b64_e32 v[152:153], v[52:53]
	s_and_b64 vcc, exec, s[6:7]
	v_mov_b64_e32 v[148:149], v[56:57]
	v_mov_b64_e32 v[146:147], v[54:55]
	v_mov_b64_e32 v[150:151], v[50:51]
	s_cbranch_vccnz .LBB0_268
	v_and_b32_e32 v147, 64, v200
	v_xor_b32_e32 v146, 16, v200
	v_add_u32_e32 v147, 64, v147
	v_cmp_lt_i32_e32 vcc, v146, v147
	v_mov_b64_e32 v[152:153], v[52:53]
	v_mov_b64_e32 v[150:151], v[50:51]
	v_cndmask_b32_e32 v146, v200, v146, vcc
	v_lshlrev_b32_e32 v146, 2, v146
	s_waitcnt lgkmcnt(3)
	ds_bpermute_b32 v190, v146, v54
	s_waitcnt lgkmcnt(3)
	ds_bpermute_b32 v186, v146, v50
	s_waitcnt lgkmcnt(3)
	ds_bpermute_b32 v191, v146, v55
	s_waitcnt lgkmcnt(3)
	ds_bpermute_b32 v187, v146, v51
	ds_bpermute_b32 v192, v146, v56
	ds_bpermute_b32 v188, v146, v52
	ds_bpermute_b32 v193, v146, v57
	ds_bpermute_b32 v189, v146, v53
	v_mov_b64_e32 v[148:149], v[56:57]
	v_mov_b64_e32 v[146:147], v[54:55]
	s_and_saveexec_b64 s[46:47], s[2:3]
	s_cbranch_execz .LBB0_267
	s_waitcnt lgkmcnt(1)
	v_pk_mul_f32 v[146:147], v[166:167], v[192:193]
	v_pk_mul_f32 v[148:149], v[164:165], v[190:191]
	s_waitcnt vmcnt(2)
	v_pk_mul_f32 v[144:145], v[144:145], v[146:147]
	v_pk_mul_f32 v[142:143], v[142:143], v[148:149]
	v_pk_fma_f32 v[148:149], v[56:57], v[136:137], v[144:145]
	v_pk_fma_f32 v[146:147], v[54:55], v[134:135], v[142:143]
	s_waitcnt lgkmcnt(0)
	v_pk_mul_f32 v[134:135], v[166:167], v[188:189]
	v_pk_mul_f32 v[136:137], v[164:165], v[186:187]
	s_waitcnt vmcnt(1)
	v_pk_mul_f32 v[134:135], v[140:141], v[134:135]
	v_pk_mul_f32 v[136:137], v[138:139], v[136:137]
	v_pk_fma_f32 v[152:153], v[52:53], v[132:133], v[134:135]
	v_pk_fma_f32 v[150:151], v[50:51], v[130:131], v[136:137]

.LBB0_268:
	s_waitcnt vmcnt(3)
	v_pk_mul_f32 v[132:133], v[184:185], v[148:149]
	v_pk_mul_f32 v[130:131], v[178:179], v[146:147]
	v_pk_mul_f32 v[134:135], v[184:185], v[152:153]
	v_pk_mul_f32 v[136:137], v[178:179], v[150:151]
	v_cvt_pk_bf16_f32 v130, v130, v131
	v_cvt_pk_bf16_f32 v131, v132, v133
	v_cvt_pk_bf16_f32 v132, v136, v137
	v_cvt_pk_bf16_f32 v133, v134, v135
	global_store_dwordx4 v[182:183], v[130:133], off offset:256 nt
	v_add_u32_e32 v182, 0x90, v176
	s_and_b64 vcc, exec, s[6:7]
	v_ashrrev_i32_e32 v183, 31, v182
	s_cbranch_vccnz .LBB0_270
	v_lshlrev_b64 v[130:131], 6, v[182:183]
	s_waitcnt vmcnt(2)
	v_lshl_add_u64 v[138:139], s[14:15], 0, v[130:131]
	global_load_dwordx4 v[134:137], v[138:139], off
	global_load_dwordx4 v[130:133], v[138:139], off offset:16
	global_load_dwordx4 v[142:145], v[138:139], off offset:32
	s_nop 0
	global_load_dwordx4 v[138:141], v[138:139], off offset:48
	s_branch .LBB0_271

.LBB0_275:
	s_waitcnt lgkmcnt(4)
	v_mov_b64_e32 v[184:185], s[16:17]
	v_mad_i64_i32 v[182:183], s[20:21], v182, s68, v[184:185]
	v_mov_b32_e32 v184, v178
	v_mov_b32_e32 v185, v178
	v_pk_mul_f32 v[148:149], v[184:185], v[148:149]
	v_pk_mul_f32 v[146:147], v[178:179], v[146:147]
	v_pk_mul_f32 v[152:153], v[184:185], v[152:153]
	v_pk_mul_f32 v[150:151], v[178:179], v[150:151]
	v_lshl_add_u64 v[182:183], v[180:181], 1, v[182:183]
	v_cvt_pk_bf16_f32 v146, v146, v147
	v_cvt_pk_bf16_f32 v147, v148, v149
	v_cvt_pk_bf16_f32 v148, v150, v151
	v_cvt_pk_bf16_f32 v149, v152, v153
	global_store_dwordx4 v[182:183], v[146:149], off nt
	v_mov_b64_e32 v[152:153], v[36:37]
	s_and_b64 vcc, exec, s[6:7]
	v_mov_b64_e32 v[148:149], v[40:41]
	v_mov_b64_e32 v[146:147], v[38:39]
	v_mov_b64_e32 v[150:151], v[34:35]
	s_cbranch_vccnz .LBB0_279
	v_and_b32_e32 v147, 64, v200
	v_xor_b32_e32 v146, 16, v200
	v_add_u32_e32 v147, 64, v147
	v_cmp_lt_i32_e32 vcc, v146, v147
	v_mov_b64_e32 v[152:153], v[36:37]
	v_mov_b64_e32 v[150:151], v[34:35]
	v_cndmask_b32_e32 v146, v200, v146, vcc
	v_lshlrev_b32_e32 v146, 2, v146
	s_waitcnt lgkmcnt(3)
	ds_bpermute_b32 v190, v146, v38
	s_waitcnt lgkmcnt(3)
	ds_bpermute_b32 v186, v146, v34
	s_waitcnt lgkmcnt(3)
	ds_bpermute_b32 v191, v146, v39
	s_waitcnt lgkmcnt(3)
	ds_bpermute_b32 v187, v146, v35
	ds_bpermute_b32 v192, v146, v40
	ds_bpermute_b32 v188, v146, v36
	ds_bpermute_b32 v193, v146, v41
	ds_bpermute_b32 v189, v146, v37
	v_mov_b64_e32 v[148:149], v[40:41]
	v_mov_b64_e32 v[146:147], v[38:39]
	s_and_saveexec_b64 s[46:47], s[2:3]
	s_cbranch_execz .LBB0_278
	s_waitcnt lgkmcnt(1)
	v_pk_mul_f32 v[146:147], v[166:167], v[192:193]
	v_pk_mul_f32 v[148:149], v[164:165], v[190:191]
	s_waitcnt vmcnt(2)
	v_pk_mul_f32 v[144:145], v[144:145], v[146:147]
	v_pk_mul_f32 v[142:143], v[142:143], v[148:149]
	v_pk_fma_f32 v[148:149], v[40:41], v[136:137], v[144:145]
	v_pk_fma_f32 v[146:147], v[38:39], v[134:135], v[142:143]
	s_waitcnt lgkmcnt(0)
	v_pk_mul_f32 v[134:135], v[166:167], v[188:189]
	v_pk_mul_f32 v[136:137], v[164:165], v[186:187]
	s_waitcnt vmcnt(1)
	v_pk_mul_f32 v[134:135], v[140:141], v[134:135]
	v_pk_mul_f32 v[136:137], v[138:139], v[136:137]
	v_pk_fma_f32 v[152:153], v[36:37], v[132:133], v[134:135]
	v_pk_fma_f32 v[150:151], v[34:35], v[130:131], v[136:137]

.LBB0_279:
	s_waitcnt vmcnt(3)
	v_pk_mul_f32 v[132:133], v[184:185], v[148:149]
	v_pk_mul_f32 v[130:131], v[178:179], v[146:147]
	v_pk_mul_f32 v[134:135], v[184:185], v[152:153]
	v_pk_mul_f32 v[136:137], v[178:179], v[150:151]
	v_cvt_pk_bf16_f32 v130, v130, v131
	v_cvt_pk_bf16_f32 v131, v132, v133
	v_cvt_pk_bf16_f32 v132, v136, v137
	v_cvt_pk_bf16_f32 v133, v134, v135
	global_store_dwordx4 v[182:183], v[130:133], off offset:256 nt
	v_add_u32_e32 v182, 0xa0, v176
	s_and_b64 vcc, exec, s[6:7]
	v_ashrrev_i32_e32 v183, 31, v182
	s_cbranch_vccnz .LBB0_281
	v_lshlrev_b64 v[130:131], 6, v[182:183]
	s_waitcnt vmcnt(2)
	v_lshl_add_u64 v[138:139], s[14:15], 0, v[130:131]
	global_load_dwordx4 v[134:137], v[138:139], off
	global_load_dwordx4 v[130:133], v[138:139], off offset:16
	global_load_dwordx4 v[142:145], v[138:139], off offset:32
	s_nop 0
	global_load_dwordx4 v[138:141], v[138:139], off offset:48
	s_branch .LBB0_282

.LBB0_286:
	s_waitcnt lgkmcnt(4)
	v_mov_b64_e32 v[184:185], s[16:17]
	v_mad_i64_i32 v[182:183], s[20:21], v182, s68, v[184:185]
	v_mov_b32_e32 v184, v178
	v_mov_b32_e32 v185, v178
	v_pk_mul_f32 v[148:149], v[184:185], v[148:149]
	v_pk_mul_f32 v[146:147], v[178:179], v[146:147]
	v_pk_mul_f32 v[152:153], v[184:185], v[152:153]
	v_pk_mul_f32 v[150:151], v[178:179], v[150:151]
	v_lshl_add_u64 v[182:183], v[180:181], 1, v[182:183]
	v_cvt_pk_bf16_f32 v146, v146, v147
	v_cvt_pk_bf16_f32 v147, v148, v149
	v_cvt_pk_bf16_f32 v148, v150, v151
	v_cvt_pk_bf16_f32 v149, v152, v153
	global_store_dwordx4 v[182:183], v[146:149], off nt
	v_mov_b64_e32 v[152:153], v[20:21]
	s_and_b64 vcc, exec, s[6:7]
	v_mov_b64_e32 v[148:149], v[24:25]
	v_mov_b64_e32 v[146:147], v[22:23]
	v_mov_b64_e32 v[150:151], v[18:19]
	s_cbranch_vccnz .LBB0_290
	v_and_b32_e32 v147, 64, v200
	v_xor_b32_e32 v146, 16, v200
	v_add_u32_e32 v147, 64, v147
	v_cmp_lt_i32_e32 vcc, v146, v147
	v_mov_b64_e32 v[152:153], v[20:21]
	v_mov_b64_e32 v[150:151], v[18:19]
	v_cndmask_b32_e32 v146, v200, v146, vcc
	v_lshlrev_b32_e32 v146, 2, v146
	s_waitcnt lgkmcnt(3)
	ds_bpermute_b32 v190, v146, v22
	s_waitcnt lgkmcnt(3)
	ds_bpermute_b32 v186, v146, v18
	s_waitcnt lgkmcnt(3)
	ds_bpermute_b32 v191, v146, v23
	s_waitcnt lgkmcnt(3)
	ds_bpermute_b32 v187, v146, v19
	ds_bpermute_b32 v192, v146, v24
	ds_bpermute_b32 v188, v146, v20
	ds_bpermute_b32 v193, v146, v25
	ds_bpermute_b32 v189, v146, v21
	v_mov_b64_e32 v[148:149], v[24:25]
	v_mov_b64_e32 v[146:147], v[22:23]
	s_and_saveexec_b64 s[46:47], s[2:3]
	s_cbranch_execz .LBB0_289
	s_waitcnt lgkmcnt(1)
	v_pk_mul_f32 v[146:147], v[166:167], v[192:193]
	v_pk_mul_f32 v[148:149], v[164:165], v[190:191]
	s_waitcnt vmcnt(2)
	v_pk_mul_f32 v[144:145], v[144:145], v[146:147]
	v_pk_mul_f32 v[142:143], v[142:143], v[148:149]
	v_pk_fma_f32 v[148:149], v[24:25], v[136:137], v[144:145]
	v_pk_fma_f32 v[146:147], v[22:23], v[134:135], v[142:143]
	s_waitcnt lgkmcnt(0)
	v_pk_mul_f32 v[134:135], v[166:167], v[188:189]
	v_pk_mul_f32 v[136:137], v[164:165], v[186:187]
	s_waitcnt vmcnt(1)
	v_pk_mul_f32 v[134:135], v[140:141], v[134:135]
	v_pk_mul_f32 v[136:137], v[138:139], v[136:137]
	v_pk_fma_f32 v[152:153], v[20:21], v[132:133], v[134:135]
	v_pk_fma_f32 v[150:151], v[18:19], v[130:131], v[136:137]

.LBB0_290:
	s_waitcnt vmcnt(3)
	v_pk_mul_f32 v[132:133], v[184:185], v[148:149]
	v_pk_mul_f32 v[130:131], v[178:179], v[146:147]
	v_pk_mul_f32 v[134:135], v[184:185], v[152:153]
	v_pk_mul_f32 v[136:137], v[178:179], v[150:151]
	v_cvt_pk_bf16_f32 v130, v130, v131
	v_cvt_pk_bf16_f32 v131, v132, v133
	v_cvt_pk_bf16_f32 v132, v136, v137
	v_cvt_pk_bf16_f32 v133, v134, v135
	global_store_dwordx4 v[182:183], v[130:133], off offset:256 nt
	v_add_u32_e32 v182, 0xb0, v176
	s_and_b64 vcc, exec, s[6:7]
	v_ashrrev_i32_e32 v183, 31, v182
	s_cbranch_vccnz .LBB0_292
	v_lshlrev_b64 v[130:131], 6, v[182:183]
	s_waitcnt vmcnt(2)
	v_lshl_add_u64 v[138:139], s[14:15], 0, v[130:131]
	global_load_dwordx4 v[134:137], v[138:139], off
	global_load_dwordx4 v[130:133], v[138:139], off offset:16
	global_load_dwordx4 v[142:145], v[138:139], off offset:32
	s_nop 0
	global_load_dwordx4 v[138:141], v[138:139], off offset:48
	s_branch .LBB0_293

.LBB0_297:
	s_waitcnt lgkmcnt(4)
	v_mov_b64_e32 v[184:185], s[16:17]
	v_mad_i64_i32 v[182:183], s[20:21], v182, s68, v[184:185]
	v_lshl_add_u64 v[180:181], v[180:181], 1, v[182:183]
	v_mov_b32_e32 v182, v178
	v_mov_b32_e32 v183, v178
	v_pk_mul_f32 v[148:149], v[182:183], v[148:149]
	v_pk_mul_f32 v[146:147], v[178:179], v[146:147]
	v_pk_mul_f32 v[152:153], v[182:183], v[152:153]
	v_pk_mul_f32 v[150:151], v[178:179], v[150:151]
	v_cvt_pk_bf16_f32 v146, v146, v147
	v_cvt_pk_bf16_f32 v147, v148, v149
	v_cvt_pk_bf16_f32 v148, v150, v151
	v_cvt_pk_bf16_f32 v149, v152, v153
	global_store_dwordx4 v[180:181], v[146:149], off nt
	v_mov_b64_e32 v[152:153], v[4:5]
	s_and_b64 vcc, exec, s[6:7]
	v_mov_b64_e32 v[148:149], v[8:9]
	v_mov_b64_e32 v[146:147], v[6:7]
	v_mov_b64_e32 v[150:151], v[2:3]
	s_cbranch_vccnz .LBB0_301
	v_and_b32_e32 v147, 64, v200
	v_xor_b32_e32 v146, 16, v200
	v_add_u32_e32 v147, 64, v147
	v_cmp_lt_i32_e32 vcc, v146, v147
	v_mov_b64_e32 v[152:153], v[4:5]
	v_mov_b64_e32 v[150:151], v[2:3]
	v_cndmask_b32_e32 v146, v200, v146, vcc
	v_lshlrev_b32_e32 v146, 2, v146
	s_waitcnt lgkmcnt(2)
	ds_bpermute_b32 v188, v146, v6
	ds_bpermute_b32 v184, v146, v2
	s_waitcnt lgkmcnt(2)
	ds_bpermute_b32 v189, v146, v7
	ds_bpermute_b32 v185, v146, v3
	ds_bpermute_b32 v190, v146, v8
	ds_bpermute_b32 v186, v146, v4
	ds_bpermute_b32 v191, v146, v9
	ds_bpermute_b32 v187, v146, v5
	v_mov_b64_e32 v[148:149], v[8:9]
	v_mov_b64_e32 v[146:147], v[6:7]
	s_and_saveexec_b64 s[6:7], s[2:3]
	s_cbranch_execz .LBB0_300
	s_waitcnt lgkmcnt(1)
	v_pk_mul_f32 v[146:147], v[166:167], v[190:191]
	v_pk_mul_f32 v[148:149], v[164:165], v[188:189]
	s_waitcnt vmcnt(2)
	v_pk_mul_f32 v[144:145], v[144:145], v[146:147]
	v_pk_mul_f32 v[142:143], v[142:143], v[148:149]
	v_pk_fma_f32 v[148:149], v[8:9], v[136:137], v[144:145]
	v_pk_fma_f32 v[146:147], v[6:7], v[134:135], v[142:143]
	s_waitcnt lgkmcnt(0)
	v_pk_mul_f32 v[134:135], v[166:167], v[186:187]
	v_pk_mul_f32 v[136:137], v[164:165], v[184:185]
	s_waitcnt vmcnt(1)
	v_pk_mul_f32 v[134:135], v[140:141], v[134:135]
	v_pk_mul_f32 v[136:137], v[138:139], v[136:137]
	v_pk_fma_f32 v[152:153], v[4:5], v[132:133], v[134:135]
	v_pk_fma_f32 v[150:151], v[2:3], v[130:131], v[136:137]

.LBB0_302:
	s_and_b64 vcc, exec, s[6:7]
	s_cbranch_vccz .LBB0_304
	v_mul_f32_e32 v122, 0xbfb8aa3b, v122
	v_mul_f32_e32 v126, 0xbfb8aa3b, v126
	v_exp_f32_e32 v122, v122
	v_mul_f32_e32 v123, 0xbfb8aa3b, v123
	v_exp_f32_e32 v134, v126
	v_exp_f32_e32 v123, v123
	v_lshl_add_u32 v162, s44, 8, v196
	v_lshlrev_b64 v[130:131], 12, v[176:177]
	v_lshl_add_u64 v[132:133], s[12:13], 0, v[130:131]
	v_lshlrev_b64 v[130:131], 1, v[162:163]
	v_mul_f32_e32 v126, 0xbfb8aa3b, v127
	v_add_f32_e32 v122, 1.0, v122
	v_exp_f32_e32 v135, v126
	v_lshl_add_u64 v[126:127], v[132:133], 0, v[130:131]
	v_add_f32_e32 v132, 1.0, v134
	v_rcp_f32_e32 v134, v122
	v_add_f32_e32 v122, 1.0, v123
	v_mul_f32_e32 v123, 0xbfb8aa3b, v124
	v_mul_f32_e32 v128, 0xbfb8aa3b, v128
	v_mul_f32_e32 v129, 0xbfb8aa3b, v129
	v_exp_f32_e32 v123, v123
	v_mul_f32_e32 v124, 0xbfb8aa3b, v125
	v_exp_f32_e32 v128, v128
	v_exp_f32_e32 v129, v129
	v_exp_f32_e32 v124, v124
	v_rcp_f32_e32 v125, v122
	v_add_f32_e32 v122, 1.0, v123
	v_add_f32_e32 v133, 1.0, v135
	v_add_f32_e32 v128, 1.0, v128
	v_add_f32_e32 v129, 1.0, v129
	v_rcp_f32_e32 v135, v122
	v_add_f32_e32 v122, 1.0, v124
	v_mul_f32_e32 v114, 0xbfb8aa3b, v114
	v_rcp_f32_e32 v132, v132
	v_rcp_f32_e32 v133, v133
	v_rcp_f32_e32 v128, v128
	v_rcp_f32_e32 v129, v129
	v_rcp_f32_e32 v136, v122
	v_exp_f32_e32 v114, v114
	v_mul_f32_e32 v115, 0xbfb8aa3b, v115
	v_exp_f32_e32 v115, v115
	v_cvt_pk_bf16_f32 v122, v132, v133
	v_cvt_pk_bf16_f32 v123, v128, v129
	v_cvt_pk_bf16_f32 v124, v134, v125
	v_cvt_pk_bf16_f32 v125, v135, v136
	v_add_f32_e32 v114, 1.0, v114
	global_store_dwordx4 v[126:127], v[122:125], off nt
	v_mul_f32_e32 v118, 0xbfb8aa3b, v118
	v_mul_f32_e32 v119, 0xbfb8aa3b, v119
	v_rcp_f32_e32 v122, v114
	v_add_f32_e32 v114, 1.0, v115
	v_mul_f32_e32 v115, 0xbfb8aa3b, v116
	v_mul_f32_e32 v120, 0xbfb8aa3b, v120
	v_mul_f32_e32 v121, 0xbfb8aa3b, v121
	v_exp_f32_e32 v115, v115
	v_mul_f32_e32 v116, 0xbfb8aa3b, v117
	v_exp_f32_e32 v118, v118
	v_exp_f32_e32 v119, v119
	v_exp_f32_e32 v120, v120
	v_exp_f32_e32 v121, v121
	v_exp_f32_e32 v116, v116
	v_rcp_f32_e32 v117, v114
	v_add_f32_e32 v114, 1.0, v115
	v_add_f32_e32 v118, 1.0, v118
	v_add_f32_e32 v119, 1.0, v119
	v_add_f32_e32 v120, 1.0, v120
	v_add_f32_e32 v121, 1.0, v121
	v_rcp_f32_e32 v123, v114
	v_add_f32_e32 v114, 1.0, v116
	v_rcp_f32_e32 v118, v118
	v_rcp_f32_e32 v119, v119
	v_rcp_f32_e32 v120, v120
	v_rcp_f32_e32 v121, v121
	v_rcp_f32_e32 v124, v114
	v_mul_f32_e32 v106, 0xbfb8aa3b, v106
	v_cvt_pk_bf16_f32 v114, v118, v119
	v_cvt_pk_bf16_f32 v115, v120, v121
	v_cvt_pk_bf16_f32 v116, v122, v117
	v_cvt_pk_bf16_f32 v117, v123, v124
	v_mul_f32_e32 v110, 0xbfb8aa3b, v110
	v_exp_f32_e32 v106, v106
	v_mul_f32_e32 v107, 0xbfb8aa3b, v107
	global_store_dwordx4 v[126:127], v[114:117], off offset:256 nt
	v_exp_f32_e32 v107, v107
	v_add_f32_e32 v106, 1.0, v106
	v_or_b32_e32 v114, 16, v176
	v_exp_f32_e32 v116, v110
	v_ashrrev_i32_e32 v115, 31, v114
	v_lshlrev_b64 v[114:115], 12, v[114:115]
	v_lshl_add_u64 v[114:115], s[12:13], 0, v[114:115]
	v_mul_f32_e32 v110, 0xbfb8aa3b, v111
	v_exp_f32_e32 v117, v110
	v_lshl_add_u64 v[110:111], v[114:115], 0, v[130:131]
	v_add_f32_e32 v114, 1.0, v116
	v_rcp_f32_e32 v116, v106
	v_add_f32_e32 v106, 1.0, v107
	v_mul_f32_e32 v107, 0xbfb8aa3b, v108
	v_mul_f32_e32 v112, 0xbfb8aa3b, v112
	v_mul_f32_e32 v113, 0xbfb8aa3b, v113
	v_exp_f32_e32 v107, v107
	v_mul_f32_e32 v108, 0xbfb8aa3b, v109
	v_exp_f32_e32 v112, v112
	v_exp_f32_e32 v113, v113
	v_exp_f32_e32 v108, v108
	v_rcp_f32_e32 v109, v106
	v_add_f32_e32 v106, 1.0, v107
	v_add_f32_e32 v115, 1.0, v117
	v_add_f32_e32 v112, 1.0, v112
	v_add_f32_e32 v113, 1.0, v113
	v_rcp_f32_e32 v117, v106
	v_add_f32_e32 v106, 1.0, v108
	v_mul_f32_e32 v98, 0xbfb8aa3b, v98
	v_rcp_f32_e32 v114, v114
	v_rcp_f32_e32 v115, v115
	v_rcp_f32_e32 v112, v112
	v_rcp_f32_e32 v113, v113
	v_rcp_f32_e32 v118, v106
	v_exp_f32_e32 v98, v98
	v_mul_f32_e32 v99, 0xbfb8aa3b, v99
	v_exp_f32_e32 v99, v99
	v_cvt_pk_bf16_f32 v106, v114, v115
	v_cvt_pk_bf16_f32 v107, v112, v113
	v_cvt_pk_bf16_f32 v108, v116, v109
	v_cvt_pk_bf16_f32 v109, v117, v118
	v_add_f32_e32 v98, 1.0, v98
	global_store_dwordx4 v[110:111], v[106:109], off nt
	v_mul_f32_e32 v102, 0xbfb8aa3b, v102
	v_mul_f32_e32 v103, 0xbfb8aa3b, v103
	v_rcp_f32_e32 v106, v98
	v_add_f32_e32 v98, 1.0, v99
	v_mul_f32_e32 v99, 0xbfb8aa3b, v100
	v_mul_f32_e32 v104, 0xbfb8aa3b, v104
	v_mul_f32_e32 v105, 0xbfb8aa3b, v105
	v_exp_f32_e32 v99, v99
	v_mul_f32_e32 v100, 0xbfb8aa3b, v101
	v_exp_f32_e32 v102, v102
	v_exp_f32_e32 v103, v103
	v_exp_f32_e32 v104, v104
	v_exp_f32_e32 v105, v105
	v_exp_f32_e32 v100, v100
	v_rcp_f32_e32 v101, v98
	v_add_f32_e32 v98, 1.0, v99
	v_add_f32_e32 v102, 1.0, v102
	v_add_f32_e32 v103, 1.0, v103
	v_add_f32_e32 v104, 1.0, v104
	v_add_f32_e32 v105, 1.0, v105
	v_rcp_f32_e32 v107, v98
	v_add_f32_e32 v98, 1.0, v100
	v_rcp_f32_e32 v102, v102
	v_rcp_f32_e32 v103, v103
	v_rcp_f32_e32 v104, v104
	v_rcp_f32_e32 v105, v105
	v_rcp_f32_e32 v108, v98
	v_mul_f32_e32 v90, 0xbfb8aa3b, v90
	v_cvt_pk_bf16_f32 v98, v102, v103
	v_cvt_pk_bf16_f32 v99, v104, v105
	v_cvt_pk_bf16_f32 v100, v106, v101
	v_cvt_pk_bf16_f32 v101, v107, v108
	v_mul_f32_e32 v94, 0xbfb8aa3b, v94
	v_exp_f32_e32 v90, v90
	v_mul_f32_e32 v91, 0xbfb8aa3b, v91
	global_store_dwordx4 v[110:111], v[98:101], off offset:256 nt
	v_exp_f32_e32 v91, v91
	v_add_f32_e32 v90, 1.0, v90
	v_or_b32_e32 v98, 32, v176
	v_exp_f32_e32 v100, v94
	v_ashrrev_i32_e32 v99, 31, v98
	v_lshlrev_b64 v[98:99], 12, v[98:99]
	v_lshl_add_u64 v[98:99], s[12:13], 0, v[98:99]
	v_mul_f32_e32 v94, 0xbfb8aa3b, v95
	v_exp_f32_e32 v101, v94
	v_lshl_add_u64 v[94:95], v[98:99], 0, v[130:131]
	v_add_f32_e32 v98, 1.0, v100
	v_rcp_f32_e32 v100, v90
	v_add_f32_e32 v90, 1.0, v91
	v_mul_f32_e32 v91, 0xbfb8aa3b, v92
	v_mul_f32_e32 v96, 0xbfb8aa3b, v96
	v_mul_f32_e32 v97, 0xbfb8aa3b, v97
	v_exp_f32_e32 v91, v91
	v_mul_f32_e32 v92, 0xbfb8aa3b, v93
	v_exp_f32_e32 v96, v96
	v_exp_f32_e32 v97, v97
	v_exp_f32_e32 v92, v92
	v_rcp_f32_e32 v93, v90
	v_add_f32_e32 v90, 1.0, v91
	v_add_f32_e32 v99, 1.0, v101
	v_add_f32_e32 v96, 1.0, v96
	v_add_f32_e32 v97, 1.0, v97
	v_rcp_f32_e32 v101, v90
	v_add_f32_e32 v90, 1.0, v92
	v_mul_f32_e32 v82, 0xbfb8aa3b, v82
	v_rcp_f32_e32 v98, v98
	v_rcp_f32_e32 v99, v99
	v_rcp_f32_e32 v96, v96
	v_rcp_f32_e32 v97, v97
	v_rcp_f32_e32 v102, v90
	v_exp_f32_e32 v82, v82
	v_mul_f32_e32 v83, 0xbfb8aa3b, v83
	v_exp_f32_e32 v83, v83
	v_cvt_pk_bf16_f32 v90, v98, v99
	v_cvt_pk_bf16_f32 v91, v96, v97
	v_cvt_pk_bf16_f32 v92, v100, v93
	v_cvt_pk_bf16_f32 v93, v101, v102
	v_add_f32_e32 v82, 1.0, v82
	global_store_dwordx4 v[94:95], v[90:93], off nt
	v_mul_f32_e32 v86, 0xbfb8aa3b, v86
	v_mul_f32_e32 v87, 0xbfb8aa3b, v87
	v_rcp_f32_e32 v90, v82
	v_add_f32_e32 v82, 1.0, v83
	v_mul_f32_e32 v83, 0xbfb8aa3b, v84
	v_mul_f32_e32 v88, 0xbfb8aa3b, v88
	v_mul_f32_e32 v89, 0xbfb8aa3b, v89
	v_exp_f32_e32 v83, v83
	v_mul_f32_e32 v84, 0xbfb8aa3b, v85
	v_exp_f32_e32 v86, v86
	v_exp_f32_e32 v87, v87
	v_exp_f32_e32 v88, v88
	v_exp_f32_e32 v89, v89
	v_exp_f32_e32 v84, v84
	v_rcp_f32_e32 v85, v82
	v_add_f32_e32 v82, 1.0, v83
	v_add_f32_e32 v86, 1.0, v86
	v_add_f32_e32 v87, 1.0, v87
	v_add_f32_e32 v88, 1.0, v88
	v_add_f32_e32 v89, 1.0, v89
	v_rcp_f32_e32 v91, v82
	v_add_f32_e32 v82, 1.0, v84
	v_rcp_f32_e32 v86, v86
	v_rcp_f32_e32 v87, v87
	v_rcp_f32_e32 v88, v88
	v_rcp_f32_e32 v89, v89
	v_rcp_f32_e32 v92, v82
	v_mul_f32_e32 v74, 0xbfb8aa3b, v74
	v_cvt_pk_bf16_f32 v82, v86, v87
	v_cvt_pk_bf16_f32 v83, v88, v89
	v_cvt_pk_bf16_f32 v84, v90, v85
	v_cvt_pk_bf16_f32 v85, v91, v92
	v_mul_f32_e32 v78, 0xbfb8aa3b, v78
	v_exp_f32_e32 v74, v74
	v_mul_f32_e32 v75, 0xbfb8aa3b, v75
	global_store_dwordx4 v[94:95], v[82:85], off offset:256 nt
	v_exp_f32_e32 v75, v75
	v_add_f32_e32 v74, 1.0, v74
	v_or_b32_e32 v82, 48, v176
	v_exp_f32_e32 v84, v78
	v_ashrrev_i32_e32 v83, 31, v82
	v_lshlrev_b64 v[82:83], 12, v[82:83]
	v_lshl_add_u64 v[82:83], s[12:13], 0, v[82:83]
	v_mul_f32_e32 v78, 0xbfb8aa3b, v79
	v_exp_f32_e32 v85, v78
	v_lshl_add_u64 v[78:79], v[82:83], 0, v[130:131]
	v_add_f32_e32 v82, 1.0, v84
	v_rcp_f32_e32 v84, v74
	v_add_f32_e32 v74, 1.0, v75
	v_mul_f32_e32 v75, 0xbfb8aa3b, v76
	v_mul_f32_e32 v80, 0xbfb8aa3b, v80
	v_mul_f32_e32 v81, 0xbfb8aa3b, v81
	v_exp_f32_e32 v75, v75
	v_mul_f32_e32 v76, 0xbfb8aa3b, v77
	v_exp_f32_e32 v80, v80
	v_exp_f32_e32 v81, v81
	v_exp_f32_e32 v76, v76
	v_rcp_f32_e32 v77, v74
	v_add_f32_e32 v74, 1.0, v75
	v_add_f32_e32 v83, 1.0, v85
	v_add_f32_e32 v80, 1.0, v80
	v_add_f32_e32 v81, 1.0, v81
	v_rcp_f32_e32 v85, v74
	v_add_f32_e32 v74, 1.0, v76
	v_mul_f32_e32 v66, 0xbfb8aa3b, v66
	v_rcp_f32_e32 v82, v82
	v_rcp_f32_e32 v83, v83
	v_rcp_f32_e32 v80, v80
	v_rcp_f32_e32 v81, v81
	v_rcp_f32_e32 v86, v74
	v_exp_f32_e32 v66, v66
	v_mul_f32_e32 v67, 0xbfb8aa3b, v67
	v_exp_f32_e32 v67, v67
	v_cvt_pk_bf16_f32 v74, v82, v83
	v_cvt_pk_bf16_f32 v75, v80, v81
	v_cvt_pk_bf16_f32 v76, v84, v77
	v_cvt_pk_bf16_f32 v77, v85, v86
	v_add_f32_e32 v66, 1.0, v66
	global_store_dwordx4 v[78:79], v[74:77], off nt
	v_mul_f32_e32 v70, 0xbfb8aa3b, v70
	v_mul_f32_e32 v71, 0xbfb8aa3b, v71
	v_rcp_f32_e32 v74, v66
	v_add_f32_e32 v66, 1.0, v67
	v_mul_f32_e32 v67, 0xbfb8aa3b, v68
	v_mul_f32_e32 v72, 0xbfb8aa3b, v72
	v_mul_f32_e32 v73, 0xbfb8aa3b, v73
	v_exp_f32_e32 v67, v67
	v_mul_f32_e32 v68, 0xbfb8aa3b, v69
	v_exp_f32_e32 v70, v70
	v_exp_f32_e32 v71, v71
	v_exp_f32_e32 v72, v72
	v_exp_f32_e32 v73, v73
	v_exp_f32_e32 v68, v68
	v_rcp_f32_e32 v69, v66
	v_add_f32_e32 v66, 1.0, v67
	v_add_f32_e32 v70, 1.0, v70
	v_add_f32_e32 v71, 1.0, v71
	v_add_f32_e32 v72, 1.0, v72
	v_add_f32_e32 v73, 1.0, v73
	v_rcp_f32_e32 v75, v66
	v_add_f32_e32 v66, 1.0, v68
	v_mul_f32_e32 v58, 0xbfb8aa3b, v58
	v_rcp_f32_e32 v70, v70
	v_rcp_f32_e32 v71, v71
	v_rcp_f32_e32 v72, v72
	v_rcp_f32_e32 v73, v73
	v_rcp_f32_e32 v76, v66
	v_exp_f32_e32 v58, v58
	v_mul_f32_e32 v59, 0xbfb8aa3b, v59
	v_exp_f32_e32 v59, v59
	v_cvt_pk_bf16_f32 v66, v70, v71
	v_cvt_pk_bf16_f32 v67, v72, v73
	v_cvt_pk_bf16_f32 v68, v74, v69
	v_cvt_pk_bf16_f32 v69, v75, v76
	v_add_f32_e32 v58, 1.0, v58
	global_store_dwordx4 v[78:79], v[66:69], off offset:256 nt
	v_mul_f32_e32 v62, 0xbfb8aa3b, v62
	v_mul_f32_e32 v64, 0xbfb8aa3b, v64
	v_mul_f32_e32 v65, 0xbfb8aa3b, v65
	v_rcp_f32_e32 v68, v58
	v_add_f32_e32 v58, 1.0, v59
	v_mul_f32_e32 v59, 0xbfb8aa3b, v60
	v_exp_f32_e32 v66, v62
	v_mul_f32_e32 v62, 0xbfb8aa3b, v63
	v_exp_f32_e32 v64, v64
	v_exp_f32_e32 v65, v65
	v_exp_f32_e32 v59, v59
	v_mul_f32_e32 v60, 0xbfb8aa3b, v61
	v_exp_f32_e32 v67, v62
	v_exp_f32_e32 v60, v60
	v_add_f32_e32 v64, 1.0, v64
	v_add_f32_e32 v65, 1.0, v65
	v_rcp_f32_e32 v61, v58
	v_add_f32_e32 v58, 1.0, v59
	v_add_f32_e32 v66, 1.0, v66
	v_add_f32_e32 v67, 1.0, v67
	v_rcp_f32_e32 v64, v64
	v_rcp_f32_e32 v65, v65
	v_rcp_f32_e32 v69, v58
	v_add_f32_e32 v58, 1.0, v60
	v_mul_f32_e32 v50, 0xbfb8aa3b, v50
	v_rcp_f32_e32 v66, v66
	v_rcp_f32_e32 v67, v67
	v_rcp_f32_e32 v70, v58
	v_exp_f32_e32 v50, v50
	v_mul_f32_e32 v51, 0xbfb8aa3b, v51
	v_exp_f32_e32 v51, v51
	v_cvt_pk_bf16_f32 v59, v64, v65
	v_add_co_u32_e32 v64, vcc, s69, v126
	v_cvt_pk_bf16_f32 v58, v66, v67
	v_cvt_pk_bf16_f32 v60, v68, v61
	v_cvt_pk_bf16_f32 v61, v69, v70
	v_addc_co_u32_e32 v65, vcc, 0, v127, vcc
	v_add_f32_e32 v50, 1.0, v50
	global_store_dwordx4 v[64:65], v[58:61], off nt
	v_mul_f32_e32 v54, 0xbfb8aa3b, v54
	v_mul_f32_e32 v55, 0xbfb8aa3b, v55
	v_rcp_f32_e32 v58, v50
	v_add_f32_e32 v50, 1.0, v51
	v_mul_f32_e32 v51, 0xbfb8aa3b, v52
	v_mul_f32_e32 v56, 0xbfb8aa3b, v56
	v_mul_f32_e32 v57, 0xbfb8aa3b, v57
	v_exp_f32_e32 v51, v51
	v_mul_f32_e32 v52, 0xbfb8aa3b, v53
	v_exp_f32_e32 v54, v54
	v_exp_f32_e32 v55, v55
	v_exp_f32_e32 v56, v56
	v_exp_f32_e32 v57, v57
	v_exp_f32_e32 v52, v52
	v_rcp_f32_e32 v53, v50
	v_add_f32_e32 v50, 1.0, v51
	v_add_f32_e32 v54, 1.0, v54
	v_add_f32_e32 v55, 1.0, v55
	v_add_f32_e32 v56, 1.0, v56
	v_add_f32_e32 v57, 1.0, v57
	v_rcp_f32_e32 v59, v50
	v_add_f32_e32 v50, 1.0, v52
	v_mul_f32_e32 v42, 0xbfb8aa3b, v42
	v_rcp_f32_e32 v54, v54
	v_rcp_f32_e32 v55, v55
	v_rcp_f32_e32 v56, v56
	v_rcp_f32_e32 v57, v57
	v_rcp_f32_e32 v60, v50
	v_exp_f32_e32 v42, v42
	v_mul_f32_e32 v43, 0xbfb8aa3b, v43
	v_exp_f32_e32 v43, v43
	v_lshl_add_u64 v[62:63], v[126:127], 0, s[26:27]
	v_cvt_pk_bf16_f32 v50, v54, v55
	v_cvt_pk_bf16_f32 v51, v56, v57
	v_cvt_pk_bf16_f32 v52, v58, v53
	v_cvt_pk_bf16_f32 v53, v59, v60
	v_add_f32_e32 v42, 1.0, v42
	global_store_dwordx4 v[62:63], v[50:53], off offset:256 nt
	v_mul_f32_e32 v46, 0xbfb8aa3b, v46
	v_mul_f32_e32 v48, 0xbfb8aa3b, v48
	v_mul_f32_e32 v49, 0xbfb8aa3b, v49
	v_rcp_f32_e32 v52, v42
	v_add_f32_e32 v42, 1.0, v43
	v_mul_f32_e32 v43, 0xbfb8aa3b, v44
	v_exp_f32_e32 v50, v46
	v_mul_f32_e32 v46, 0xbfb8aa3b, v47
	v_exp_f32_e32 v48, v48
	v_exp_f32_e32 v49, v49
	v_exp_f32_e32 v43, v43
	v_mul_f32_e32 v44, 0xbfb8aa3b, v45
	v_exp_f32_e32 v51, v46
	v_exp_f32_e32 v44, v44
	v_add_f32_e32 v48, 1.0, v48
	v_add_f32_e32 v49, 1.0, v49
	v_rcp_f32_e32 v45, v42
	v_add_f32_e32 v42, 1.0, v43
	v_add_f32_e32 v50, 1.0, v50
	v_add_f32_e32 v51, 1.0, v51
	v_rcp_f32_e32 v48, v48
	v_rcp_f32_e32 v49, v49
	v_rcp_f32_e32 v53, v42
	v_add_f32_e32 v42, 1.0, v44
	v_mul_f32_e32 v34, 0xbfb8aa3b, v34
	v_rcp_f32_e32 v50, v50
	v_rcp_f32_e32 v51, v51
	v_rcp_f32_e32 v54, v42
	v_exp_f32_e32 v34, v34
	v_mul_f32_e32 v35, 0xbfb8aa3b, v35
	v_exp_f32_e32 v35, v35
	v_cvt_pk_bf16_f32 v43, v48, v49
	v_add_co_u32_e32 v48, vcc, s70, v126
	v_cvt_pk_bf16_f32 v42, v50, v51
	v_cvt_pk_bf16_f32 v44, v52, v45
	v_cvt_pk_bf16_f32 v45, v53, v54
	v_addc_co_u32_e32 v49, vcc, 0, v127, vcc
	v_add_f32_e32 v34, 1.0, v34
	global_store_dwordx4 v[48:49], v[42:45], off nt
	v_mul_f32_e32 v38, 0xbfb8aa3b, v38
	v_mul_f32_e32 v39, 0xbfb8aa3b, v39
	v_rcp_f32_e32 v42, v34
	v_add_f32_e32 v34, 1.0, v35
	v_mul_f32_e32 v35, 0xbfb8aa3b, v36
	v_mul_f32_e32 v40, 0xbfb8aa3b, v40
	v_mul_f32_e32 v41, 0xbfb8aa3b, v41
	v_exp_f32_e32 v35, v35
	v_mul_f32_e32 v36, 0xbfb8aa3b, v37
	v_exp_f32_e32 v38, v38
	v_exp_f32_e32 v39, v39
	v_exp_f32_e32 v40, v40
	v_exp_f32_e32 v41, v41
	v_exp_f32_e32 v36, v36
	v_rcp_f32_e32 v37, v34
	v_add_f32_e32 v34, 1.0, v35
	v_add_f32_e32 v38, 1.0, v38
	v_add_f32_e32 v39, 1.0, v39
	v_add_f32_e32 v40, 1.0, v40
	v_add_f32_e32 v41, 1.0, v41
	v_rcp_f32_e32 v43, v34
	v_add_f32_e32 v34, 1.0, v36
	v_mul_f32_e32 v26, 0xbfb8aa3b, v26
	v_rcp_f32_e32 v38, v38
	v_rcp_f32_e32 v39, v39
	v_rcp_f32_e32 v40, v40
	v_rcp_f32_e32 v41, v41
	v_rcp_f32_e32 v44, v34
	v_exp_f32_e32 v26, v26
	v_mul_f32_e32 v27, 0xbfb8aa3b, v27
	v_exp_f32_e32 v27, v27
	v_lshl_add_u64 v[46:47], v[126:127], 0, s[28:29]
	v_cvt_pk_bf16_f32 v34, v38, v39
	v_cvt_pk_bf16_f32 v35, v40, v41
	v_cvt_pk_bf16_f32 v36, v42, v37
	v_cvt_pk_bf16_f32 v37, v43, v44
	v_add_f32_e32 v26, 1.0, v26
	global_store_dwordx4 v[46:47], v[34:37], off offset:256 nt
	v_mul_f32_e32 v30, 0xbfb8aa3b, v30
	v_mul_f32_e32 v32, 0xbfb8aa3b, v32
	v_mul_f32_e32 v33, 0xbfb8aa3b, v33
	v_rcp_f32_e32 v36, v26
	v_add_f32_e32 v26, 1.0, v27
	v_mul_f32_e32 v27, 0xbfb8aa3b, v28
	v_exp_f32_e32 v34, v30
	v_mul_f32_e32 v30, 0xbfb8aa3b, v31
	v_exp_f32_e32 v32, v32
	v_exp_f32_e32 v33, v33
	v_exp_f32_e32 v27, v27
	v_mul_f32_e32 v28, 0xbfb8aa3b, v29
	v_exp_f32_e32 v35, v30
	v_exp_f32_e32 v28, v28
	v_add_f32_e32 v32, 1.0, v32
	v_add_f32_e32 v33, 1.0, v33
	v_rcp_f32_e32 v29, v26
	v_add_f32_e32 v26, 1.0, v27
	v_add_f32_e32 v34, 1.0, v34
	v_add_f32_e32 v35, 1.0, v35
	v_rcp_f32_e32 v32, v32
	v_rcp_f32_e32 v33, v33
	v_rcp_f32_e32 v37, v26
	v_add_f32_e32 v26, 1.0, v28
	v_mul_f32_e32 v18, 0xbfb8aa3b, v18
	v_rcp_f32_e32 v34, v34
	v_rcp_f32_e32 v35, v35
	v_rcp_f32_e32 v38, v26
	v_exp_f32_e32 v18, v18
	v_mul_f32_e32 v19, 0xbfb8aa3b, v19
	v_exp_f32_e32 v19, v19
	v_cvt_pk_bf16_f32 v27, v32, v33
	v_add_co_u32_e32 v32, vcc, s71, v126
	v_cvt_pk_bf16_f32 v26, v34, v35
	v_cvt_pk_bf16_f32 v28, v36, v29
	v_cvt_pk_bf16_f32 v29, v37, v38
	v_addc_co_u32_e32 v33, vcc, 0, v127, vcc
	v_add_f32_e32 v18, 1.0, v18
	global_store_dwordx4 v[32:33], v[26:29], off nt
	v_mul_f32_e32 v22, 0xbfb8aa3b, v22
	v_mul_f32_e32 v23, 0xbfb8aa3b, v23
	v_rcp_f32_e32 v26, v18
	v_add_f32_e32 v18, 1.0, v19
	v_mul_f32_e32 v19, 0xbfb8aa3b, v20
	v_mul_f32_e32 v24, 0xbfb8aa3b, v24
	v_mul_f32_e32 v25, 0xbfb8aa3b, v25
	v_exp_f32_e32 v19, v19
	v_mul_f32_e32 v20, 0xbfb8aa3b, v21
	v_exp_f32_e32 v22, v22
	v_exp_f32_e32 v23, v23
	v_exp_f32_e32 v24, v24
	v_exp_f32_e32 v25, v25
	v_exp_f32_e32 v20, v20
	v_rcp_f32_e32 v21, v18
	v_add_f32_e32 v18, 1.0, v19
	v_add_f32_e32 v22, 1.0, v22
	v_add_f32_e32 v23, 1.0, v23
	v_add_f32_e32 v24, 1.0, v24
	v_add_f32_e32 v25, 1.0, v25
	v_rcp_f32_e32 v27, v18
	v_add_f32_e32 v18, 1.0, v20
	v_mul_f32_e32 v10, 0xbfb8aa3b, v10
	v_rcp_f32_e32 v22, v22
	v_rcp_f32_e32 v23, v23
	v_rcp_f32_e32 v24, v24
	v_rcp_f32_e32 v25, v25
	v_rcp_f32_e32 v28, v18
	v_exp_f32_e32 v10, v10
	v_mul_f32_e32 v11, 0xbfb8aa3b, v11
	v_exp_f32_e32 v11, v11
	v_lshl_add_u64 v[30:31], v[126:127], 0, s[30:31]
	v_cvt_pk_bf16_f32 v18, v22, v23
	v_cvt_pk_bf16_f32 v19, v24, v25
	v_cvt_pk_bf16_f32 v20, v26, v21
	v_cvt_pk_bf16_f32 v21, v27, v28
	v_add_f32_e32 v10, 1.0, v10
	global_store_dwordx4 v[30:31], v[18:21], off offset:256 nt
	v_mul_f32_e32 v14, 0xbfb8aa3b, v14
	v_mul_f32_e32 v15, 0xbfb8aa3b, v15
	v_rcp_f32_e32 v18, v10
	v_add_f32_e32 v10, 1.0, v11
	v_mul_f32_e32 v11, 0xbfb8aa3b, v12
	v_exp_f32_e32 v14, v14
	v_exp_f32_e32 v15, v15
	v_mul_f32_e32 v16, 0xbfb8aa3b, v16
	v_mul_f32_e32 v17, 0xbfb8aa3b, v17
	v_exp_f32_e32 v11, v11
	v_mul_f32_e32 v12, 0xbfb8aa3b, v13
	v_mul_f32_e32 v6, 0xbfb8aa3b, v6
	v_mul_f32_e32 v7, 0xbfb8aa3b, v7
	v_mul_f32_e32 v8, 0xbfb8aa3b, v8
	v_mul_f32_e32 v9, 0xbfb8aa3b, v9
	v_mul_f32_e32 v2, 0xbfb8aa3b, v2
	v_mul_f32_e32 v3, 0xbfb8aa3b, v3
	v_mul_f32_e32 v4, 0xbfb8aa3b, v4
	v_exp_f32_e32 v16, v16
	v_exp_f32_e32 v17, v17
	v_exp_f32_e32 v12, v12
	v_exp_f32_e32 v6, v6
	v_exp_f32_e32 v7, v7
	v_exp_f32_e32 v8, v8
	v_exp_f32_e32 v9, v9
	v_exp_f32_e32 v2, v2
	v_exp_f32_e32 v3, v3
	v_exp_f32_e32 v4, v4
	v_mul_f32_e32 v5, 0xbfb8aa3b, v5
	v_exp_f32_e32 v5, v5
	v_add_f32_e32 v14, 1.0, v14
	v_add_f32_e32 v15, 1.0, v15
	v_rcp_f32_e32 v13, v10
	v_add_f32_e32 v10, 1.0, v11
	v_rcp_f32_e32 v14, v14
	v_rcp_f32_e32 v15, v15
	v_add_f32_e32 v16, 1.0, v16
	v_add_f32_e32 v17, 1.0, v17
	v_rcp_f32_e32 v19, v10
	v_add_f32_e32 v10, 1.0, v12
	v_add_f32_e32 v6, 1.0, v6
	v_add_f32_e32 v7, 1.0, v7
	v_add_f32_e32 v8, 1.0, v8
	v_add_f32_e32 v9, 1.0, v9
	v_add_f32_e32 v2, 1.0, v2
	v_add_f32_e32 v3, 1.0, v3
	v_add_f32_e32 v4, 1.0, v4
	v_rcp_f32_e32 v16, v16
	v_rcp_f32_e32 v17, v17
	v_rcp_f32_e32 v20, v10
	v_rcp_f32_e32 v6, v6
	v_rcp_f32_e32 v7, v7
	v_rcp_f32_e32 v8, v8
	v_rcp_f32_e32 v9, v9
	v_rcp_f32_e32 v2, v2
	v_rcp_f32_e32 v3, v3
	v_rcp_f32_e32 v134, v4
	v_add_f32_e32 v4, 1.0, v5
	v_rcp_f32_e32 v135, v4
	v_cvt_pk_bf16_f32 v10, v14, v15
	v_add_co_u32_e32 v14, vcc, s72, v126
	v_lshl_add_u64 v[180:181], v[126:127], 0, s[34:35]
	v_cvt_pk_bf16_f32 v11, v16, v17
	v_cvt_pk_bf16_f32 v12, v18, v13
	v_cvt_pk_bf16_f32 v13, v19, v20
	v_addc_co_u32_e32 v15, vcc, 0, v127, vcc
	v_cvt_pk_bf16_f32 v130, v6, v7
	v_cvt_pk_bf16_f32 v131, v8, v9
	v_cvt_pk_bf16_f32 v132, v2, v3
	global_store_dwordx4 v[14:15], v[10:13], off nt
.LBB0_304:
	v_cvt_pk_bf16_f32 v133, v134, v135
	s_andn2_b64 vcc, exec, s[4:5]
	s_mov_b64 s[4:5], -1
	global_store_dwordx4 v[180:181], v[130:133], off offset:256 nt
	s_cbranch_vccnz .LBB0_205
	s_andn2_b64 vcc, exec, s[8:9]
	s_cbranch_vccnz .LBB0_204
	s_barrier
	s_branch .LBB0_204

.LBB0_433:
	v_and_b32_e32 v2, 31, v223
	v_ashrrev_i32_e32 v8, 5, v223
	v_lshrrev_b32_e32 v9, 1, v223
	v_lshlrev_b32_e32 v10, 7, v2
	v_bitop3_b32 v11, v9, v8, 7 bitop3:0x6c
	v_lshl_add_u32 v226, v11, 4, v10
	v_add_u32_e32 v11, 2, v8
	v_bitop3_b32 v11, v11, v9, 7 bitop3:0x78
	v_lshl_add_u32 v227, v11, 4, v10
	v_add_u32_e32 v11, 4, v8
	v_bitop3_b32 v11, v11, v9, 7 bitop3:0x78
	s_add_i32 s2, s3, 0
	v_lshl_add_u32 v228, v11, 4, v10
	v_add_u32_e32 v11, 6, v8
	s_add_i32 s2, s2, 0x10800
	v_bitop3_b32 v9, v11, v9, 7 bitop3:0x78
	v_lshl_add_u32 v230, v9, 4, v10
	v_mov_b32_e32 v9, s2
	s_and_b32 s2, s5, 0x3fffffc0
	s_lshl_b32 s2, s2, 2
	s_add_i32 s56, s2, 0
	s_lshl_b32 s2, s46, 1
	s_add_i32 s56, s56, 0x10000
	s_and_b32 s5, s2, 0x700
	s_add_u32 s5, s7, s5
	v_mad_u32_u24 v18, v2, s49, v9
	v_lshl_add_u32 v229, v2, 2, s56
	s_addc_u32 s7, s6, 0
	s_mul_i32 s6, s4, 0xa800
	v_mul_lo_u32 v2, v4, s48
	v_add_u32_e32 v2, s6, v2
	s_add_u32 s6, s12, s5
	v_or_b32_e32 v2, v2, v7
	s_addc_u32 s7, s13, s7
	s_mov_b64 s[72:73], s[6:7]
	v_lshlrev_b32_e32 v225, 4, v8
	v_bfe_u32 v9, v223, 2, 2
	v_lshlrev_b32_e32 v8, 10, v8
	v_lshlrev_b32_e32 v10, 5, v5
	v_lshlrev_b32_e32 v11, 3, v223
	v_lshl_add_u64 v[210:211], v[2:3], 1, s[6:7]
	v_lshlrev_b32_e32 v254, 1, v2
	s_mulk_i32 s4, 0x5400
	v_mul_lo_u32 v2, v5, s48
	v_lshl_or_b32 v8, v9, 8, v8
	v_and_b32_e32 v10, 32, v10
	v_and_b32_e32 v11, 24, v11
	v_add_u32_e32 v2, s4, v2
	v_or3_b32 v8, v8, v10, v11
	v_lshlrev_b32_e32 v9, 6, v9
	v_or_b32_e32 v2, v2, v6
	v_mov_b32_e32 v16, v3
	v_mov_b32_e32 v17, v3
	v_or_b32_e32 v231, v8, v9
	v_bitop3_b32 v232, v8, 64, v9 bitop3:0x36
	v_bitop3_b32 v233, v8, s51, v9 bitop3:0x36
	v_bitop3_b32 v234, v8, s52, v9 bitop3:0x36
	v_lshl_add_u64 v[212:213], v[2:3], 1, s[6:7]
	v_lshlrev_b32_e32 v255, 1, v2
	v_mov_b32_e32 v2, v3
	v_mov_b32_e32 v4, v3
	v_mov_b32_e32 v5, v3
	v_mov_b32_e32 v6, v3
	v_mov_b32_e32 v7, v3
	v_mov_b32_e32 v8, v3
	v_mov_b32_e32 v9, v3
	v_mov_b32_e32 v10, v3
	v_mov_b32_e32 v11, v3
	v_mov_b32_e32 v12, v3
	v_mov_b32_e32 v13, v3
	v_mov_b32_e32 v14, v3
	v_mov_b32_e32 v15, v3
	v_add_u32_e32 v236, v18, v225
	v_mov_b64_e32 v[96:97], v[16:17]
	v_mov_b64_e32 v[80:81], v[16:17]
	v_mov_b64_e32 v[48:49], v[16:17]
	v_mov_b64_e32 v[32:33], v[16:17]
	v_mov_b64_e32 v[144:145], v[16:17]
	v_mov_b64_e32 v[128:129], v[16:17]
	v_mov_b64_e32 v[112:113], v[16:17]
	v_mov_b64_e32 v[64:65], v[16:17]
	v_cmp_gt_u32_e64 s[2:3], 32, v223
	s_mov_b32 s57, 0
	v_mov_b32_e32 v235, 0
	s_mov_b64 s[42:43], 0
	v_mov_b64_e32 v[94:95], v[14:15]
	v_mov_b64_e32 v[92:93], v[12:13]
	v_mov_b64_e32 v[90:91], v[10:11]
	v_mov_b64_e32 v[88:89], v[8:9]
	v_mov_b64_e32 v[86:87], v[6:7]
	v_mov_b64_e32 v[84:85], v[4:5]
	v_mov_b64_e32 v[82:83], v[2:3]
	v_mov_b64_e32 v[78:79], v[14:15]
	v_mov_b64_e32 v[76:77], v[12:13]
	v_mov_b64_e32 v[74:75], v[10:11]
	v_mov_b64_e32 v[72:73], v[8:9]
	v_mov_b64_e32 v[70:71], v[6:7]
	v_mov_b64_e32 v[68:69], v[4:5]
	v_mov_b64_e32 v[66:67], v[2:3]
	v_mov_b64_e32 v[46:47], v[14:15]
	v_mov_b64_e32 v[44:45], v[12:13]
	v_mov_b64_e32 v[42:43], v[10:11]
	v_mov_b64_e32 v[40:41], v[8:9]
	v_mov_b64_e32 v[38:39], v[6:7]
	v_mov_b64_e32 v[36:37], v[4:5]
	v_mov_b64_e32 v[34:35], v[2:3]
	v_mov_b64_e32 v[30:31], v[14:15]
	v_mov_b64_e32 v[28:29], v[12:13]
	v_mov_b64_e32 v[26:27], v[10:11]
	v_mov_b64_e32 v[24:25], v[8:9]
	v_mov_b64_e32 v[22:23], v[6:7]
	v_mov_b64_e32 v[20:21], v[4:5]
	v_mov_b64_e32 v[18:19], v[2:3]
	v_mov_b64_e32 v[142:143], v[14:15]
	v_mov_b64_e32 v[140:141], v[12:13]
	v_mov_b64_e32 v[138:139], v[10:11]
	v_mov_b64_e32 v[136:137], v[8:9]
	v_mov_b64_e32 v[134:135], v[6:7]
	v_mov_b64_e32 v[132:133], v[4:5]
	v_mov_b64_e32 v[130:131], v[2:3]
	v_mov_b64_e32 v[126:127], v[14:15]
	v_mov_b64_e32 v[124:125], v[12:13]
	v_mov_b64_e32 v[122:123], v[10:11]
	v_mov_b64_e32 v[120:121], v[8:9]
	v_mov_b64_e32 v[118:119], v[6:7]
	v_mov_b64_e32 v[116:117], v[4:5]
	v_mov_b64_e32 v[114:115], v[2:3]
	v_mov_b64_e32 v[110:111], v[14:15]
	v_mov_b64_e32 v[108:109], v[12:13]
	v_mov_b64_e32 v[106:107], v[10:11]
	v_mov_b64_e32 v[104:105], v[8:9]
	v_mov_b64_e32 v[102:103], v[6:7]
	v_mov_b64_e32 v[100:101], v[4:5]
	v_mov_b64_e32 v[98:99], v[2:3]
	v_mov_b64_e32 v[62:63], v[14:15]
	v_mov_b64_e32 v[60:61], v[12:13]
	v_mov_b64_e32 v[58:59], v[10:11]
	v_mov_b64_e32 v[56:57], v[8:9]
	v_mov_b64_e32 v[54:55], v[6:7]
	v_mov_b64_e32 v[52:53], v[4:5]
	v_mov_b64_e32 v[50:51], v[2:3]
	v_mov_b32_e32 v4, 0
	v_mov_b32_e32 v5, v224
	s_cmp_lg_u32 s68, 0
	s_cbranch_scc1 .LBB0_435
	s_add_u32 s74, s72, s30
	s_addc_u32 s75, s73, s31
	s_add_u32 s76, s72, s36
	s_addc_u32 s77, s73, s37
	s_branch .LBB0_435_f

.LBB0_435_f:
	s_waitcnt vmcnt(0)
	s_barrier
	s_add_u32 s80, s74, s42
	s_addc_u32 s81, s75, s43
	s_add_i32 s4, s55, 0x8000
	s_mov_b32 m0, s4
	s_add_u32 s82, s76, s42
	s_addc_u32 s83, s77, s43
	global_load_lds_dwordx4 v254, s[80:81]
	s_add_i32 m0, s4, 0x1f80
	s_add_u32 s84, s82, 0x54000
	s_addc_u32 s85, s83, 0
	global_load_lds_dwordx4 v254, s[80:81] offset:128
	s_add_i32 m0, s4, 0x4000
	s_nop 0
	global_load_lds_dwordx4 v255, s[82:83]
	s_add_i32 m0, s4, 0x6000
	s_nop 0
	global_load_lds_dwordx4 v255, s[84:85]
	ds_read_b128 v[6:9], v236
	ds_read_b128 v[178:181], v226
	ds_read_b128 v[182:185], v226 offset:4096
	ds_read_b128 v[10:13], v236 offset:32
	ds_read_b128 v[186:189], v227
	ds_read_b128 v[190:193], v227 offset:4096
	ds_read_b128 v[14:17], v236 offset:64
	ds_read_b128 v[194:197], v228
	ds_read_b128 v[198:201], v228 offset:4096
	ds_read_b128 v[238:241], v236 offset:96
	ds_read_b128 v[202:205], v230
	ds_read_b128 v[206:209], v230 offset:4096
	s_waitcnt lgkmcnt(9)
	v_mfma_f32_32x32x16_bf16 v[162:177], v[178:181], v[6:9], 0
	v_mfma_f32_32x32x16_bf16 v[146:161], v[182:185], v[6:9], 0
	ds_read_b128 v[246:249], v236 offset:128
	ds_read_b128 v[250:253], v226 offset:8192
	ds_read_b128 v[6:9], v226 offset:12288
	s_waitcnt lgkmcnt(9)
	v_mfma_f32_32x32x16_bf16 v[162:177], v[186:189], v[10:13], v[162:177]
	v_mfma_f32_32x32x16_bf16 v[146:161], v[190:193], v[10:13], v[146:161]
	ds_read_b128 v[10:13], v236 offset:160
	s_waitcnt lgkmcnt(7)
	v_mfma_f32_32x32x16_bf16 v[162:177], v[194:197], v[14:17], v[162:177]
	v_mfma_f32_32x32x16_bf16 v[146:161], v[198:201], v[14:17], v[146:161]
	ds_read_b128 v[14:17], v227 offset:8192
	s_waitcnt lgkmcnt(5)
	v_mfma_f32_32x32x16_bf16 v[162:177], v[202:205], v[238:241], v[162:177]
	v_mfma_f32_32x32x16_bf16 v[146:161], v[206:209], v[238:241], v[146:161]
	ds_read_b128 v[238:241], v227 offset:12288
	s_waitcnt lgkmcnt(3)
	v_mfma_f32_32x32x16_bf16 v[194:209], v[250:253], v[246:249], 0
	v_mfma_f32_32x32x16_bf16 v[178:193], v[6:9], v[246:249], 0
	ds_read_b128 v[246:249], v236 offset:192
	ds_read_b128 v[250:253], v228 offset:8192
	ds_read_b128 v[6:9], v228 offset:12288
	s_waitcnt lgkmcnt(3)
	v_mfma_f32_32x32x16_bf16 v[194:209], v[14:17], v[10:13], v[194:209]
	v_mfma_f32_32x32x16_bf16 v[178:193], v[238:241], v[10:13], v[178:193]
	ds_read_b128 v[10:13], v236 offset:224
	ds_read_b128 v[14:17], v230 offset:8192
	ds_read_b128 v[238:241], v230 offset:12288
	s_waitcnt lgkmcnt(3)
	v_mfma_f32_32x32x16_bf16 v[194:209], v[250:253], v[246:249], v[194:209]
	v_mfma_f32_32x32x16_bf16 v[178:193], v[6:9], v[246:249], v[178:193]
	s_waitcnt lgkmcnt(0)
	v_mfma_f32_32x32x16_bf16 v[194:209], v[14:17], v[10:13], v[194:209]
	v_mfma_f32_32x32x16_bf16 v[178:193], v[238:241], v[10:13], v[178:193]
	v_exp_f32_e32 v166, v166
	v_exp_f32_e32 v167, v167
	v_exp_f32_e32 v168, v168
	v_exp_f32_e32 v169, v169
	s_nop 6
	v_exp_f32_e32 v2, v194
	v_exp_f32_e32 v194, v195
	v_exp_f32_e32 v195, v196
	v_exp_f32_e32 v196, v197
	v_exp_f32_e32 v197, v198
	v_exp_f32_e32 v198, v199
	v_exp_f32_e32 v199, v200
	v_exp_f32_e32 v200, v201
	v_exp_f32_e32 v201, v162
	v_exp_f32_e32 v237, v163
	v_exp_f32_e32 v238, v164
	v_exp_f32_e32 v239, v165
	v_cvt_pk_bf16_f32 v6, v201, v237
	v_cvt_pk_bf16_f32 v7, v238, v239
	v_cvt_pk_bf16_f32 v8, v166, v167
	v_cvt_pk_bf16_f32 v9, v168, v169
	ds_read_b64_tr_b16 v[10:11], v231 offset:16384
	ds_read_b64_tr_b16 v[12:13], v231 offset:18432
	v_cvt_pk_bf16_f32 v14, v2, v194
	ds_read_b64_tr_b16 v[162:163], v232 offset:16384
	ds_read_b64_tr_b16 v[164:165], v232 offset:18432
	v_cvt_pk_bf16_f32 v15, v195, v196
	v_cvt_pk_bf16_f32 v16, v197, v198
	v_cvt_pk_bf16_f32 v17, v199, v200
	s_waitcnt lgkmcnt(2)
	v_mfma_f32_32x32x16_bf16 v[82:97], v[6:9], v[10:13], v[82:97]
	v_exp_f32_e32 v202, v202
	v_exp_f32_e32 v203, v203
	v_exp_f32_e32 v204, v204
	v_exp_f32_e32 v205, v205
	v_exp_f32_e32 v206, v206
	v_exp_f32_e32 v207, v207
	v_exp_f32_e32 v208, v208
	v_mfma_f32_32x32x16_bf16 v[130:145], v[14:17], v[10:13], v[130:145]
	ds_read_b64_tr_b16 v[10:11], v233 offset:16384
	ds_read_b64_tr_b16 v[12:13], v233 offset:18432
	v_exp_f32_e32 v170, v170
	v_exp_f32_e32 v171, v171
	v_exp_f32_e32 v172, v172
	v_exp_f32_e32 v173, v173
	v_exp_f32_e32 v174, v174
	v_exp_f32_e32 v175, v175
	s_waitcnt lgkmcnt(2)
	v_mfma_f32_32x32x16_bf16 v[66:81], v[6:9], v[162:165], v[66:81]
	v_exp_f32_e32 v176, v176
	v_exp_f32_e32 v177, v177
	v_exp_f32_e32 v209, v209
	v_exp_f32_e32 v178, v178
	v_exp_f32_e32 v179, v179
	v_exp_f32_e32 v180, v180
	v_exp_f32_e32 v181, v181
	v_mfma_f32_32x32x16_bf16 v[114:129], v[14:17], v[162:165], v[114:129]
	ds_read_b64_tr_b16 v[162:163], v234 offset:16384
	ds_read_b64_tr_b16 v[164:165], v234 offset:18432
	v_add_f32_e32 v2, v178, v2
	v_add_f32_e32 v2, 0, v2
	v_add_f32_e32 v194, v179, v194
	v_add_f32_e32 v2, v194, v2
	v_add_f32_e32 v194, v180, v195
	s_waitcnt lgkmcnt(2)
	v_mfma_f32_32x32x16_bf16 v[34:49], v[6:9], v[10:13], v[34:49]
	v_add_f32_e32 v2, v194, v2
	v_add_f32_e32 v194, v181, v196
	v_add_f32_e32 v2, v194, v2
	v_exp_f32_e32 v182, v182
	v_exp_f32_e32 v183, v183
	v_exp_f32_e32 v184, v184
	v_exp_f32_e32 v194, v146
	v_mfma_f32_32x32x16_bf16 v[98:113], v[14:17], v[10:13], v[98:113]
	ds_read_b64_tr_b16 v[10:11], v231 offset:20480
	ds_read_b64_tr_b16 v[12:13], v231 offset:22528
	v_exp_f32_e32 v195, v147
	v_exp_f32_e32 v196, v148
	v_exp_f32_e32 v244, v149
	v_exp_f32_e32 v150, v150
	v_exp_f32_e32 v151, v151
	v_exp_f32_e32 v152, v152
	s_waitcnt lgkmcnt(2)
	v_mfma_f32_32x32x16_bf16 v[18:33], v[6:9], v[162:165], v[18:33]
	v_cvt_pk_bf16_f32 v6, v170, v171
	v_cvt_pk_bf16_f32 v7, v172, v173
	v_cvt_pk_bf16_f32 v8, v174, v175
	v_cvt_pk_bf16_f32 v9, v176, v177
	v_exp_f32_e32 v153, v153
	v_exp_f32_e32 v154, v154
	v_exp_f32_e32 v155, v155
	v_mfma_f32_32x32x16_bf16 v[50:65], v[14:17], v[162:165], v[50:65]
	v_cvt_pk_bf16_f32 v14, v202, v203
	ds_read_b64_tr_b16 v[162:163], v232 offset:20480
	ds_read_b64_tr_b16 v[164:165], v232 offset:22528
	v_cvt_pk_bf16_f32 v15, v204, v205
	v_cvt_pk_bf16_f32 v16, v206, v207
	v_cvt_pk_bf16_f32 v17, v208, v209
	v_exp_f32_e32 v156, v156
	s_waitcnt lgkmcnt(2)
	v_mfma_f32_32x32x16_bf16 v[82:97], v[6:9], v[10:13], v[82:97]
	v_exp_f32_e32 v157, v157
	v_exp_f32_e32 v158, v158
	v_exp_f32_e32 v159, v159
	v_exp_f32_e32 v160, v160
	v_exp_f32_e32 v161, v161
	s_add_u32 s42, s42, 0xa8000
	s_addc_u32 s43, s43, 0
	v_mfma_f32_32x32x16_bf16 v[130:145], v[14:17], v[10:13], v[130:145]
	ds_read_b64_tr_b16 v[10:11], v233 offset:20480
	ds_read_b64_tr_b16 v[12:13], v233 offset:22528
	s_waitcnt lgkmcnt(2)
	v_mfma_f32_32x32x16_bf16 v[66:81], v[6:9], v[162:165], v[66:81]
	v_mfma_f32_32x32x16_bf16 v[114:129], v[14:17], v[162:165], v[114:129]
	ds_read_b64_tr_b16 v[162:163], v234 offset:20480
	ds_read_b64_tr_b16 v[164:165], v234 offset:22528
	s_waitcnt lgkmcnt(0)
	v_mfma_f32_32x32x16_bf16 v[18:33], v[6:9], v[162:165], v[18:33]
	v_mfma_f32_32x32x16_bf16 v[50:65], v[14:17], v[162:165], v[50:65]
	v_exp_f32_e32 v162, v185
	v_add_f32_e32 v163, v182, v197
	v_add_f32_e32 v2, v163, v2
	v_add_f32_e32 v163, v183, v198
	v_add_f32_e32 v2, v163, v2
	v_exp_f32_e32 v163, v186
	v_exp_f32_e32 v164, v188
	v_mfma_f32_32x32x16_bf16 v[34:49], v[6:9], v[10:13], v[34:49]
	v_cvt_pk_bf16_f32 v6, v194, v195
	v_cvt_pk_bf16_f32 v7, v196, v244
	v_cvt_pk_bf16_f32 v8, v150, v151
	v_cvt_pk_bf16_f32 v9, v152, v153
	v_exp_f32_e32 v165, v189
	v_mfma_f32_32x32x16_bf16 v[98:113], v[14:17], v[10:13], v[98:113]
	ds_read_b64_tr_b16 v[10:11], v231 offset:24576
	ds_read_b64_tr_b16 v[12:13], v231 offset:26624
	v_cvt_pk_bf16_f32 v14, v178, v179
	v_cvt_pk_bf16_f32 v15, v180, v181
	v_cvt_pk_bf16_f32 v16, v182, v183
	v_cvt_pk_bf16_f32 v17, v184, v162
	ds_read_b64_tr_b16 v[146:147], v232 offset:24576
	ds_read_b64_tr_b16 v[148:149], v232 offset:26624
	v_add_f32_e32 v178, v165, v205
	s_waitcnt lgkmcnt(2)
	v_mfma_f32_32x32x16_bf16 v[82:97], v[6:9], v[10:13], v[82:97]
	v_exp_f32_e32 v179, v190
	s_nop 0
	v_add_f32_e32 v180, v179, v206
	v_mfma_f32_32x32x16_bf16 v[130:145], v[14:17], v[10:13], v[130:145]
	v_add_f32_e32 v10, v184, v199
	v_add_f32_e32 v2, v10, v2
	v_add_f32_e32 v10, v162, v200
	v_exp_f32_e32 v162, v187
	v_add_f32_e32 v2, v10, v2
	v_add_f32_e32 v10, v163, v202
	v_add_f32_e32 v2, v10, v2
	v_add_f32_e32 v10, v162, v203
	v_add_f32_e32 v2, v10, v2
	v_add_f32_e32 v10, v164, v204
	v_add_f32_e32 v2, v10, v2
	v_add_f32_e32 v2, v178, v2
	v_exp_f32_e32 v178, v191
	ds_read_b64_tr_b16 v[10:11], v233 offset:24576
	ds_read_b64_tr_b16 v[12:13], v233 offset:26624
	s_waitcnt lgkmcnt(2)
	v_mfma_f32_32x32x16_bf16 v[66:81], v[6:9], v[146:149], v[66:81]
	v_add_f32_e32 v2, v180, v2
	v_exp_f32_e32 v180, v192
	v_add_f32_e32 v181, v178, v207
	v_add_f32_e32 v2, v181, v2
	v_exp_f32_e32 v181, v193
	v_mfma_f32_32x32x16_bf16 v[114:129], v[14:17], v[146:149], v[114:129]
	ds_read_b64_tr_b16 v[146:147], v234 offset:24576
	ds_read_b64_tr_b16 v[148:149], v234 offset:26624
	s_waitcnt lgkmcnt(2)
	v_mfma_f32_32x32x16_bf16 v[34:49], v[6:9], v[10:13], v[34:49]
	v_mfma_f32_32x32x16_bf16 v[98:113], v[14:17], v[10:13], v[98:113]
	v_add_f32_e32 v10, v180, v208
	v_add_f32_e32 v2, v10, v2
	ds_read_b64_tr_b16 v[10:11], v231 offset:28672
	ds_read_b64_tr_b16 v[12:13], v231 offset:30720
	s_waitcnt lgkmcnt(2)
	v_mfma_f32_32x32x16_bf16 v[18:33], v[6:9], v[146:149], v[18:33]
	v_cvt_pk_bf16_f32 v6, v154, v155
	v_cvt_pk_bf16_f32 v7, v156, v157
	v_cvt_pk_bf16_f32 v8, v158, v159
	v_cvt_pk_bf16_f32 v9, v160, v161
	v_mfma_f32_32x32x16_bf16 v[50:65], v[14:17], v[146:149], v[50:65]
	v_cvt_pk_bf16_f32 v14, v163, v162
	v_cvt_pk_bf16_f32 v15, v164, v165
	v_cvt_pk_bf16_f32 v16, v179, v178
	v_cvt_pk_bf16_f32 v17, v180, v181
	v_add_f32_e32 v162, v181, v209
	v_add_f32_e32 v2, v162, v2
	v_add_f32_e32 v4, v4, v2
	v_add_f32_e32 v2, v194, v201
	s_waitcnt lgkmcnt(0)
	v_mfma_f32_32x32x16_bf16 v[82:97], v[6:9], v[10:13], v[82:97]
	v_add_f32_e32 v2, 0, v2
	ds_read_b64_tr_b16 v[146:147], v232 offset:28672
	ds_read_b64_tr_b16 v[148:149], v232 offset:30720
	v_mfma_f32_32x32x16_bf16 v[130:145], v[14:17], v[10:13], v[130:145]
	v_add_f32_e32 v10, v195, v237
	v_add_f32_e32 v2, v10, v2
	v_add_f32_e32 v10, v196, v238
	v_add_f32_e32 v2, v10, v2
	v_add_f32_e32 v10, v244, v239
	v_add_f32_e32 v2, v10, v2
	v_add_f32_e32 v10, v150, v166
	v_add_f32_e32 v2, v10, v2
	v_add_f32_e32 v10, v151, v167
	v_add_f32_e32 v2, v10, v2
	v_add_f32_e32 v10, v152, v168
	s_waitcnt lgkmcnt(0)
	v_mfma_f32_32x32x16_bf16 v[66:81], v[6:9], v[146:149], v[66:81]
	v_add_f32_e32 v2, v10, v2
	ds_read_b64_tr_b16 v[10:11], v233 offset:28672
	ds_read_b64_tr_b16 v[12:13], v233 offset:30720
	v_add_f32_e32 v150, v153, v169
	v_add_f32_e32 v2, v150, v2
	v_add_f32_e32 v150, v154, v170
	v_add_f32_e32 v2, v150, v2
	v_add_f32_e32 v150, v155, v171
	v_mfma_f32_32x32x16_bf16 v[114:129], v[14:17], v[146:149], v[114:129]
	ds_read_b64_tr_b16 v[146:147], v234 offset:28672
	ds_read_b64_tr_b16 v[148:149], v234 offset:30720
	v_add_f32_e32 v2, v150, v2
	v_add_f32_e32 v150, v156, v172
	v_add_f32_e32 v2, v150, v2
	v_add_f32_e32 v150, v157, v173
	v_add_f32_e32 v2, v150, v2
	s_waitcnt lgkmcnt(2)
	v_mfma_f32_32x32x16_bf16 v[34:49], v[6:9], v[10:13], v[34:49]
	v_mfma_f32_32x32x16_bf16 v[98:113], v[14:17], v[10:13], v[98:113]
	v_add_f32_e32 v10, v158, v174
	v_add_f32_e32 v2, v10, v2
	v_add_f32_e32 v10, v159, v175
	v_add_f32_e32 v2, v10, v2
	v_add_f32_e32 v10, v160, v176
	v_add_f32_e32 v2, v10, v2
	v_add_f32_e32 v10, v161, v177
	s_waitcnt lgkmcnt(0)
	v_mfma_f32_32x32x16_bf16 v[18:33], v[6:9], v[146:149], v[18:33]
	v_add_f32_e32 v2, v10, v2
	v_add_f32_e32 v235, v235, v2
	v_mfma_f32_32x32x16_bf16 v[50:65], v[14:17], v[146:149], v[50:65]
	s_waitcnt vmcnt(0)
	s_barrier
	s_cmp_eq_u32 s42, 0x5358000
	s_cbranch_scc1 .Lskip_dma_f
	s_add_u32 s80, s74, s42
	s_addc_u32 s81, s75, s43
	s_add_i32 s4, s55, 0
	s_mov_b32 m0, s4
	s_add_u32 s82, s76, s42
	s_addc_u32 s83, s77, s43
	global_load_lds_dwordx4 v254, s[80:81]
	s_add_i32 m0, s4, 0x1f80
	s_add_u32 s84, s82, 0x54000
	s_addc_u32 s85, s83, 0
	global_load_lds_dwordx4 v254, s[80:81] offset:128
	s_add_i32 m0, s4, 0x4000
	s_nop 0
	global_load_lds_dwordx4 v255, s[82:83]
	s_add_i32 m0, s4, 0x6000
	s_nop 0
	global_load_lds_dwordx4 v255, s[84:85]
.Lskip_dma_f:
	ds_read_b128 v[6:9], v236
	ds_read_b128 v[178:181], v226 offset:32768
	ds_read_b128 v[182:185], v226 offset:36864
	ds_read_b128 v[10:13], v236 offset:32
	ds_read_b128 v[186:189], v227 offset:32768
	ds_read_b128 v[190:193], v227 offset:36864
	ds_read_b128 v[14:17], v236 offset:64
	ds_read_b128 v[194:197], v228 offset:32768
	ds_read_b128 v[198:201], v228 offset:36864
	ds_read_b128 v[238:241], v236 offset:96
	ds_read_b128 v[202:205], v230 offset:32768
	ds_read_b128 v[206:209], v230 offset:36864
	s_waitcnt lgkmcnt(9)
	v_mfma_f32_32x32x16_bf16 v[162:177], v[178:181], v[6:9], 0
	v_mfma_f32_32x32x16_bf16 v[146:161], v[182:185], v[6:9], 0
	ds_read_b128 v[246:249], v236 offset:128
	ds_read_b128 v[250:253], v226 offset:40960
	ds_read_b128 v[6:9], v226 offset:45056
	s_waitcnt lgkmcnt(9)
	v_mfma_f32_32x32x16_bf16 v[162:177], v[186:189], v[10:13], v[162:177]
	v_mfma_f32_32x32x16_bf16 v[146:161], v[190:193], v[10:13], v[146:161]
	ds_read_b128 v[10:13], v236 offset:160
	s_waitcnt lgkmcnt(7)
	v_mfma_f32_32x32x16_bf16 v[162:177], v[194:197], v[14:17], v[162:177]
	v_mfma_f32_32x32x16_bf16 v[146:161], v[198:201], v[14:17], v[146:161]
	ds_read_b128 v[14:17], v227 offset:40960
	s_waitcnt lgkmcnt(5)
	v_mfma_f32_32x32x16_bf16 v[162:177], v[202:205], v[238:241], v[162:177]
	v_mfma_f32_32x32x16_bf16 v[146:161], v[206:209], v[238:241], v[146:161]
	ds_read_b128 v[238:241], v227 offset:45056
	s_waitcnt lgkmcnt(3)
	v_mfma_f32_32x32x16_bf16 v[194:209], v[250:253], v[246:249], 0
	v_mfma_f32_32x32x16_bf16 v[178:193], v[6:9], v[246:249], 0
	ds_read_b128 v[246:249], v236 offset:192
	ds_read_b128 v[250:253], v228 offset:40960
	ds_read_b128 v[6:9], v228 offset:45056
	s_waitcnt lgkmcnt(3)
	v_mfma_f32_32x32x16_bf16 v[194:209], v[14:17], v[10:13], v[194:209]
	v_mfma_f32_32x32x16_bf16 v[178:193], v[238:241], v[10:13], v[178:193]
	ds_read_b128 v[10:13], v236 offset:224
	ds_read_b128 v[14:17], v230 offset:40960
	ds_read_b128 v[238:241], v230 offset:45056
	s_waitcnt lgkmcnt(3)
	v_mfma_f32_32x32x16_bf16 v[194:209], v[250:253], v[246:249], v[194:209]
	v_mfma_f32_32x32x16_bf16 v[178:193], v[6:9], v[246:249], v[178:193]
	s_waitcnt lgkmcnt(0)
	v_mfma_f32_32x32x16_bf16 v[194:209], v[14:17], v[10:13], v[194:209]
	v_mfma_f32_32x32x16_bf16 v[178:193], v[238:241], v[10:13], v[178:193]
	v_exp_f32_e32 v166, v166
	v_exp_f32_e32 v167, v167
	v_exp_f32_e32 v168, v168
	v_exp_f32_e32 v169, v169
	s_nop 6
	v_exp_f32_e32 v2, v194
	v_exp_f32_e32 v194, v195
	v_exp_f32_e32 v195, v196
	v_exp_f32_e32 v196, v197
	v_exp_f32_e32 v197, v198
	v_exp_f32_e32 v198, v199
	v_exp_f32_e32 v199, v200
	v_exp_f32_e32 v200, v201
	v_exp_f32_e32 v201, v162
	v_exp_f32_e32 v237, v163
	v_exp_f32_e32 v238, v164
	v_exp_f32_e32 v239, v165
	v_cvt_pk_bf16_f32 v6, v201, v237
	v_cvt_pk_bf16_f32 v7, v238, v239
	v_cvt_pk_bf16_f32 v8, v166, v167
	v_cvt_pk_bf16_f32 v9, v168, v169
	ds_read_b64_tr_b16 v[10:11], v231 offset:49152
	ds_read_b64_tr_b16 v[12:13], v231 offset:51200
	v_cvt_pk_bf16_f32 v14, v2, v194
	ds_read_b64_tr_b16 v[162:163], v232 offset:49152
	ds_read_b64_tr_b16 v[164:165], v232 offset:51200
	v_cvt_pk_bf16_f32 v15, v195, v196
	v_cvt_pk_bf16_f32 v16, v197, v198
	v_cvt_pk_bf16_f32 v17, v199, v200
	s_waitcnt lgkmcnt(2)
	v_mfma_f32_32x32x16_bf16 v[82:97], v[6:9], v[10:13], v[82:97]
	v_exp_f32_e32 v202, v202
	v_exp_f32_e32 v203, v203
	v_exp_f32_e32 v204, v204
	v_exp_f32_e32 v205, v205
	v_exp_f32_e32 v206, v206
	v_exp_f32_e32 v207, v207
	v_exp_f32_e32 v208, v208
	v_mfma_f32_32x32x16_bf16 v[130:145], v[14:17], v[10:13], v[130:145]
	ds_read_b64_tr_b16 v[10:11], v233 offset:49152
	ds_read_b64_tr_b16 v[12:13], v233 offset:51200
	v_exp_f32_e32 v170, v170
	v_exp_f32_e32 v171, v171
	v_exp_f32_e32 v172, v172
	v_exp_f32_e32 v173, v173
	v_exp_f32_e32 v174, v174
	v_exp_f32_e32 v175, v175
	s_waitcnt lgkmcnt(2)
	v_mfma_f32_32x32x16_bf16 v[66:81], v[6:9], v[162:165], v[66:81]
	v_exp_f32_e32 v176, v176
	v_exp_f32_e32 v177, v177
	v_exp_f32_e32 v209, v209
	v_exp_f32_e32 v178, v178
	v_exp_f32_e32 v179, v179
	v_exp_f32_e32 v180, v180
	v_exp_f32_e32 v181, v181
	v_mfma_f32_32x32x16_bf16 v[114:129], v[14:17], v[162:165], v[114:129]
	ds_read_b64_tr_b16 v[162:163], v234 offset:49152
	ds_read_b64_tr_b16 v[164:165], v234 offset:51200
	v_add_f32_e32 v2, v178, v2
	v_add_f32_e32 v2, 0, v2
	v_add_f32_e32 v194, v179, v194
	v_add_f32_e32 v2, v194, v2
	v_add_f32_e32 v194, v180, v195
	s_waitcnt lgkmcnt(2)
	v_mfma_f32_32x32x16_bf16 v[34:49], v[6:9], v[10:13], v[34:49]
	v_add_f32_e32 v2, v194, v2
	v_add_f32_e32 v194, v181, v196
	v_add_f32_e32 v2, v194, v2
	v_exp_f32_e32 v182, v182
	v_exp_f32_e32 v183, v183
	v_exp_f32_e32 v184, v184
	v_exp_f32_e32 v194, v146
	v_mfma_f32_32x32x16_bf16 v[98:113], v[14:17], v[10:13], v[98:113]
	ds_read_b64_tr_b16 v[10:11], v231 offset:53248
	ds_read_b64_tr_b16 v[12:13], v231 offset:55296
	v_exp_f32_e32 v195, v147
	v_exp_f32_e32 v196, v148
	v_exp_f32_e32 v244, v149
	v_exp_f32_e32 v150, v150
	v_exp_f32_e32 v151, v151
	v_exp_f32_e32 v152, v152
	s_waitcnt lgkmcnt(2)
	v_mfma_f32_32x32x16_bf16 v[18:33], v[6:9], v[162:165], v[18:33]
	v_cvt_pk_bf16_f32 v6, v170, v171
	v_cvt_pk_bf16_f32 v7, v172, v173
	v_cvt_pk_bf16_f32 v8, v174, v175
	v_cvt_pk_bf16_f32 v9, v176, v177
	v_exp_f32_e32 v153, v153
	v_exp_f32_e32 v154, v154
	v_exp_f32_e32 v155, v155
	v_mfma_f32_32x32x16_bf16 v[50:65], v[14:17], v[162:165], v[50:65]
	v_cvt_pk_bf16_f32 v14, v202, v203
	ds_read_b64_tr_b16 v[162:163], v232 offset:53248
	ds_read_b64_tr_b16 v[164:165], v232 offset:55296
	v_cvt_pk_bf16_f32 v15, v204, v205
	v_cvt_pk_bf16_f32 v16, v206, v207
	v_cvt_pk_bf16_f32 v17, v208, v209
	v_exp_f32_e32 v156, v156
	s_waitcnt lgkmcnt(2)
	v_mfma_f32_32x32x16_bf16 v[82:97], v[6:9], v[10:13], v[82:97]
	v_exp_f32_e32 v157, v157
	v_exp_f32_e32 v158, v158
	v_exp_f32_e32 v159, v159
	v_exp_f32_e32 v160, v160
	v_exp_f32_e32 v161, v161
	s_add_u32 s42, s42, 0xa8000
	s_addc_u32 s43, s43, 0
	v_mfma_f32_32x32x16_bf16 v[130:145], v[14:17], v[10:13], v[130:145]
	ds_read_b64_tr_b16 v[10:11], v233 offset:53248
	ds_read_b64_tr_b16 v[12:13], v233 offset:55296
	s_cmp_eq_u32 s42, 0x5400000
	s_waitcnt lgkmcnt(2)
	v_mfma_f32_32x32x16_bf16 v[66:81], v[6:9], v[162:165], v[66:81]
	v_mfma_f32_32x32x16_bf16 v[114:129], v[14:17], v[162:165], v[114:129]
	ds_read_b64_tr_b16 v[162:163], v234 offset:53248
	ds_read_b64_tr_b16 v[164:165], v234 offset:55296
	s_waitcnt lgkmcnt(0)
	v_mfma_f32_32x32x16_bf16 v[18:33], v[6:9], v[162:165], v[18:33]
	v_mfma_f32_32x32x16_bf16 v[50:65], v[14:17], v[162:165], v[50:65]
	v_exp_f32_e32 v162, v185
	v_add_f32_e32 v163, v182, v197
	v_add_f32_e32 v2, v163, v2
	v_add_f32_e32 v163, v183, v198
	v_add_f32_e32 v2, v163, v2
	v_exp_f32_e32 v163, v186
	v_exp_f32_e32 v164, v188
	v_mfma_f32_32x32x16_bf16 v[34:49], v[6:9], v[10:13], v[34:49]
	v_cvt_pk_bf16_f32 v6, v194, v195
	v_cvt_pk_bf16_f32 v7, v196, v244
	v_cvt_pk_bf16_f32 v8, v150, v151
	v_cvt_pk_bf16_f32 v9, v152, v153
	v_exp_f32_e32 v165, v189
	v_mfma_f32_32x32x16_bf16 v[98:113], v[14:17], v[10:13], v[98:113]
	ds_read_b64_tr_b16 v[10:11], v231 offset:57344
	ds_read_b64_tr_b16 v[12:13], v231 offset:59392
	v_cvt_pk_bf16_f32 v14, v178, v179
	v_cvt_pk_bf16_f32 v15, v180, v181
	v_cvt_pk_bf16_f32 v16, v182, v183
	v_cvt_pk_bf16_f32 v17, v184, v162
	ds_read_b64_tr_b16 v[146:147], v232 offset:57344
	ds_read_b64_tr_b16 v[148:149], v232 offset:59392
	v_add_f32_e32 v178, v165, v205
	s_waitcnt lgkmcnt(2)
	v_mfma_f32_32x32x16_bf16 v[82:97], v[6:9], v[10:13], v[82:97]
	v_exp_f32_e32 v179, v190
	s_nop 0
	v_add_f32_e32 v180, v179, v206
	v_mfma_f32_32x32x16_bf16 v[130:145], v[14:17], v[10:13], v[130:145]
	v_add_f32_e32 v10, v184, v199
	v_add_f32_e32 v2, v10, v2
	v_add_f32_e32 v10, v162, v200
	v_exp_f32_e32 v162, v187
	v_add_f32_e32 v2, v10, v2
	v_add_f32_e32 v10, v163, v202
	v_add_f32_e32 v2, v10, v2
	v_add_f32_e32 v10, v162, v203
	v_add_f32_e32 v2, v10, v2
	v_add_f32_e32 v10, v164, v204
	v_add_f32_e32 v2, v10, v2
	v_add_f32_e32 v2, v178, v2
	v_exp_f32_e32 v178, v191
	ds_read_b64_tr_b16 v[10:11], v233 offset:57344
	ds_read_b64_tr_b16 v[12:13], v233 offset:59392
	s_waitcnt lgkmcnt(2)
	v_mfma_f32_32x32x16_bf16 v[66:81], v[6:9], v[146:149], v[66:81]
	v_add_f32_e32 v2, v180, v2
	v_exp_f32_e32 v180, v192
	v_add_f32_e32 v181, v178, v207
	v_add_f32_e32 v2, v181, v2
	v_exp_f32_e32 v181, v193
	v_mfma_f32_32x32x16_bf16 v[114:129], v[14:17], v[146:149], v[114:129]
	ds_read_b64_tr_b16 v[146:147], v234 offset:57344
	ds_read_b64_tr_b16 v[148:149], v234 offset:59392
	s_waitcnt lgkmcnt(2)
	v_mfma_f32_32x32x16_bf16 v[34:49], v[6:9], v[10:13], v[34:49]
	v_mfma_f32_32x32x16_bf16 v[98:113], v[14:17], v[10:13], v[98:113]
	v_add_f32_e32 v10, v180, v208
	v_add_f32_e32 v2, v10, v2
	ds_read_b64_tr_b16 v[10:11], v231 offset:61440
	ds_read_b64_tr_b16 v[12:13], v231 offset:63488
	s_waitcnt lgkmcnt(2)
	v_mfma_f32_32x32x16_bf16 v[18:33], v[6:9], v[146:149], v[18:33]
	v_cvt_pk_bf16_f32 v6, v154, v155
	v_cvt_pk_bf16_f32 v7, v156, v157
	v_cvt_pk_bf16_f32 v8, v158, v159
	v_cvt_pk_bf16_f32 v9, v160, v161
	v_mfma_f32_32x32x16_bf16 v[50:65], v[14:17], v[146:149], v[50:65]
	v_cvt_pk_bf16_f32 v14, v163, v162
	v_cvt_pk_bf16_f32 v15, v164, v165
	v_cvt_pk_bf16_f32 v16, v179, v178
	v_cvt_pk_bf16_f32 v17, v180, v181
	v_add_f32_e32 v162, v181, v209
	v_add_f32_e32 v2, v162, v2
	v_add_f32_e32 v4, v4, v2
	v_add_f32_e32 v2, v194, v201
	s_waitcnt lgkmcnt(0)
	v_mfma_f32_32x32x16_bf16 v[82:97], v[6:9], v[10:13], v[82:97]
	v_add_f32_e32 v2, 0, v2
	ds_read_b64_tr_b16 v[146:147], v232 offset:61440
	ds_read_b64_tr_b16 v[148:149], v232 offset:63488
	v_mfma_f32_32x32x16_bf16 v[130:145], v[14:17], v[10:13], v[130:145]
	v_add_f32_e32 v10, v195, v237
	v_add_f32_e32 v2, v10, v2
	v_add_f32_e32 v10, v196, v238
	v_add_f32_e32 v2, v10, v2
	v_add_f32_e32 v10, v244, v239
	v_add_f32_e32 v2, v10, v2
	v_add_f32_e32 v10, v150, v166
	v_add_f32_e32 v2, v10, v2
	v_add_f32_e32 v10, v151, v167
	v_add_f32_e32 v2, v10, v2
	v_add_f32_e32 v10, v152, v168
	s_waitcnt lgkmcnt(0)
	v_mfma_f32_32x32x16_bf16 v[66:81], v[6:9], v[146:149], v[66:81]
	v_add_f32_e32 v2, v10, v2
	ds_read_b64_tr_b16 v[10:11], v233 offset:61440
	ds_read_b64_tr_b16 v[12:13], v233 offset:63488
	v_add_f32_e32 v150, v153, v169
	v_add_f32_e32 v2, v150, v2
	v_add_f32_e32 v150, v154, v170
	v_add_f32_e32 v2, v150, v2
	v_add_f32_e32 v150, v155, v171
	v_mfma_f32_32x32x16_bf16 v[114:129], v[14:17], v[146:149], v[114:129]
	ds_read_b64_tr_b16 v[146:147], v234 offset:61440
	ds_read_b64_tr_b16 v[148:149], v234 offset:63488
	v_add_f32_e32 v2, v150, v2
	v_add_f32_e32 v150, v156, v172
	v_add_f32_e32 v2, v150, v2
	v_add_f32_e32 v150, v157, v173
	v_add_f32_e32 v2, v150, v2
	s_waitcnt lgkmcnt(2)
	v_mfma_f32_32x32x16_bf16 v[34:49], v[6:9], v[10:13], v[34:49]
	v_mfma_f32_32x32x16_bf16 v[98:113], v[14:17], v[10:13], v[98:113]
	v_add_f32_e32 v10, v158, v174
	v_add_f32_e32 v2, v10, v2
	v_add_f32_e32 v10, v159, v175
	v_add_f32_e32 v2, v10, v2
	v_add_f32_e32 v10, v160, v176
	v_add_f32_e32 v2, v10, v2
	v_add_f32_e32 v10, v161, v177
	s_waitcnt lgkmcnt(0)
	v_mfma_f32_32x32x16_bf16 v[18:33], v[6:9], v[146:149], v[18:33]
	v_add_f32_e32 v2, v10, v2
	v_add_f32_e32 v235, v235, v2
	v_mfma_f32_32x32x16_bf16 v[50:65], v[14:17], v[146:149], v[50:65]
	s_cbranch_scc0 .LBB0_435_f
